# P4 retention-unit output: column groups exchanged between lanes l and l^16 (v_permlane16_swap), four 16-byte plain stores per lane instead of eight 8-byte ones; on top of v6
# speedup vs baseline: 1.0004x; 1.0004x over previous
; #define LAS __attribute__((address_space(3)))
; __device__ __forceinline__ float log_sigmoid(float x) { return -log1pf(expf(-x)); }
; __device__ __forceinline__ void ret_unit(LAS unsigned char* lds, int u, const bf16* PROJ, const int* pos, const float* dec_f, const float* dec_b, const bf16* ST,
;                                          const float* gn_w, const float* gn_b, bf16* MIX, int tid, const WsRef& wsr) {
;     ...
;     const int bh = u >> 6, c = u & 63, b = bh >> 2, h = bh & 3;
;     const size_t row0 = (size_t)b * SEQ + (size_t)c * 128;
;     LAS bf16* Qs = (LAS bf16*)lds; LAS bf16* Ks = (LAS bf16*)(lds + TILE_B); LAS bf16* VT = (LAS bf16*)(lds + 2 * TILE_B);
;     const float lgf2 = log_sigmoid(dec_f[h]) * LOG2E, lgb2 = log_sigmoid(dec_b[h]) * LOG2E;
.LBB0_438:
	s_ashr_i32 s0, s73, 6
	s_and_b32 s80, s0, 3
	s_lshl_b32 s1, s80, 2
	v_mov_b32_e32 v16, s1
	global_load_dword v0, v16, s[18:19]
	s_mov_b32 s1, 0x42ce8ed0
	s_mov_b32 s83, 0xc2b17218
	s_mov_b32 s11, 0x3f2aaaab
	s_mov_b32 s88, 0x7f800000
	s_mov_b32 s8, 0x33800000
	s_and_b32 s82, s73, 63
	s_ashr_i32 s4, s73, 8
	s_ashr_i32 s5, s4, 31
	s_lshl_b32 s81, s82, 7
	s_waitcnt vmcnt(0)
	v_mul_f32_e32 v1, 0xbfb8aa3b, v0
	v_fma_f32 v2, v0, s41, -v1
	v_rndne_f32_e32 v3, v1
	v_fmac_f32_e32 v2, 0xb2a5705f, v0
	v_sub_f32_e32 v1, v1, v3
	v_add_f32_e32 v1, v1, v2
	v_exp_f32_e32 v1, v1
	v_cvt_i32_f32_e32 v2, v3
	v_cmp_nlt_f32_e64 s[68:69], s1, v0
	v_ldexp_f32 v1, v1, v2
	s_nop 0
	v_cndmask_b32_e64 v1, 0, v1, s[68:69]
	v_cmp_ngt_f32_e64 s[68:69], s83, v0
	s_nop 1
	v_cndmask_b32_e64 v17, v228, v1, s[68:69]
	v_add_f32_e32 v2, 1.0, v17
	v_add_f32_e32 v0, -1.0, v2
	v_sub_f32_e32 v1, v0, v2
	v_add_f32_e32 v1, 1.0, v1
	v_sub_f32_e32 v0, v17, v0
	v_add_f32_e32 v3, v0, v1
	v_frexp_mant_f32_e32 v0, v2
	v_cmp_gt_f32_e64 s[68:69], s11, v0
	v_cvt_f64_f32_e32 v[0:1], v2
	v_frexp_exp_i32_f64_e32 v0, v[0:1]
	v_subbrev_co_u32_e64 v8, s[68:69], 0, v0, s[68:69]
	v_sub_u32_e32 v0, 0, v8
	v_ldexp_f32 v1, v2, v0
	v_add_f32_e32 v2, -1.0, v1
	v_add_f32_e32 v4, 1.0, v1
	v_ldexp_f32 v0, v3, v0
	v_add_f32_e32 v3, 1.0, v2
	v_add_f32_e32 v5, -1.0, v4
	v_sub_f32_e32 v3, v1, v3
	v_sub_f32_e32 v1, v1, v5
	v_add_f32_e32 v3, v0, v3
	v_add_f32_e32 v0, v0, v1
	v_add_f32_e32 v9, v4, v0
	v_rcp_f32_e32 v11, v9
	v_sub_f32_e32 v1, v4, v9
	v_add_f32_e32 v10, v0, v1
	v_add_f32_e32 v1, v2, v3
	v_mul_f32_e32 v13, v1, v11
	v_sub_f32_e32 v0, v2, v1
	v_mul_f32_e32 v2, v9, v13
	v_fma_f32 v4, v13, v9, -v2
	v_fmac_f32_e32 v4, v13, v10
	v_add_f32_e32 v12, v3, v0
	v_add_f32_e32 v0, v2, v4
	v_sub_f32_e32 v3, v1, v0
	v_pk_add_f32 v[6:7], v[0:1], v[2:3] neg_lo:[0,1] neg_hi:[0,1]
	v_mov_b32_e32 v5, v0
	v_pk_add_f32 v[0:1], v[6:7], v[4:5] neg_lo:[0,1] neg_hi:[0,1]
	v_cmp_neq_f32_e64 s[68:69], s88, v17
	v_add_f32_e32 v1, v12, v1
	v_add_f32_e32 v0, v0, v1
	v_add_f32_e32 v1, v3, v0
	v_mul_f32_e32 v12, v11, v1
	v_mul_f32_e32 v2, v9, v12
	v_fma_f32 v4, v12, v9, -v2
	v_fmac_f32_e32 v4, v12, v10
	v_sub_f32_e32 v3, v3, v1
	v_add_f32_e32 v9, v0, v3
	v_add_f32_e32 v0, v2, v4
	v_sub_f32_e32 v3, v1, v0
	v_pk_add_f32 v[6:7], v[0:1], v[2:3] neg_lo:[0,1] neg_hi:[0,1]
	v_mov_b32_e32 v5, v0
	v_pk_add_f32 v[0:1], v[6:7], v[4:5] neg_lo:[0,1] neg_hi:[0,1]
	s_nop 0
	v_add_f32_e32 v1, v9, v1
	v_add_f32_e32 v0, v0, v1
	v_add_f32_e32 v1, v13, v12
	v_add_f32_e32 v0, v3, v0
	v_sub_f32_e32 v2, v1, v13
	v_mul_f32_e32 v0, v11, v0
	v_sub_f32_e32 v2, v12, v2
	v_add_f32_e32 v2, v2, v0
	v_add_f32_e32 v4, v1, v2
	v_mul_f32_e32 v5, v4, v4
	v_fmamk_f32 v0, v5, 0x3e9b6dac, v223
	v_fmaak_f32 v105, v5, v0, 0x3f2aaada
	v_cvt_f32_i32_e32 v0, v8
	v_sub_f32_e32 v1, v4, v1
	v_sub_f32_e32 v1, v2, v1
	v_ldexp_f32 v6, v1, 1
	v_mul_f32_e32 v1, v4, v5
	v_ldexp_f32 v3, v4, 1
	v_pk_mul_f32 v[4:5], v[0:1], v[104:105]
	s_nop 0
	v_fma_f32 v2, v0, s33, -v4
	v_fmac_f32_e32 v2, 0xb102e308, v0
	v_pk_add_f32 v[0:1], v[4:5], v[2:3]
	s_nop 0
	v_sub_f32_e32 v3, v1, v3
	v_sub_f32_e32 v3, v5, v3
	v_add_f32_e32 v7, v6, v3
	v_mov_b32_e32 v6, v4
	v_pk_add_f32 v[4:5], v[0:1], v[4:5] neg_lo:[0,1] neg_hi:[0,1]
	v_pk_add_f32 v[8:9], v[0:1], v[6:7]
	v_mov_b32_e32 v3, v0
	v_mov_b32_e32 v5, v9
	v_pk_add_f32 v[10:11], v[2:3], v[4:5] neg_lo:[0,1] neg_hi:[0,1]
	v_pk_add_f32 v[2:3], v[2:3], v[4:5]
	v_mov_b32_e32 v14, v1
	v_pk_add_f32 v[4:5], v[2:3], v[0:1] op_sel:[1,0] op_sel_hi:[0,1] neg_lo:[0,1] neg_hi:[0,1]
	v_pk_add_f32 v[12:13], v[8:9], v[4:5] op_sel_hi:[1,0] neg_lo:[0,1] neg_hi:[0,1]
	v_mov_b32_e32 v8, v9
	v_mov_b32_e32 v9, v3
	v_mov_b32_e32 v15, v4
	v_pk_add_f32 v[4:5], v[8:9], v[14:15] neg_lo:[0,1] neg_hi:[0,1]
	v_mov_b32_e32 v6, v7
	v_mov_b32_e32 v7, v0
	v_pk_add_f32 v[0:1], v[6:7], v[4:5] neg_lo:[0,1] neg_hi:[0,1]
	v_mov_b32_e32 v12, v10
	v_pk_add_f32 v[4:5], v[12:13], v[0:1]
	v_mov_b32_e32 v11, v3
	v_pk_add_f32 v[6:7], v[4:5], v[4:5] op_sel:[0,1] op_sel_hi:[1,0]
	s_nop 0
	v_pk_add_f32 v[2:3], v[2:3], v[6:7] op_sel:[1,0] op_sel_hi:[0,1]
	v_mov_b32_e32 v5, v2
	v_pk_add_f32 v[8:9], v[4:5], v[10:11] neg_lo:[0,1] neg_hi:[0,1]
	v_mov_b32_e32 v1, v6
	v_sub_f32_e32 v3, v4, v8
	v_pk_add_f32 v[0:1], v[0:1], v[8:9] neg_lo:[0,1] neg_hi:[0,1]
	v_sub_f32_e32 v3, v10, v3
	v_add_f32_e32 v0, v0, v3
	v_add_f32_e32 v0, v0, v1
	global_load_dword v1, v16, s[20:21]
	v_add_f32_e32 v0, v2, v0
	v_cndmask_b32_e64 v0, v228, v0, s[68:69]
	v_cmp_lt_f32_e64 s[68:69], |v17|, s8
	s_waitcnt vmcnt(0)
; __device__ __forceinline__ u32x4 ws_load16(const WsRef& w, unsigned byte_off) { return __builtin_bit_cast(u32x4, __builtin_amdgcn_raw_buffer_load_b128(w.r, byte_off, 0, 0)); }
; __device__ __forceinline__ float log_sigmoid(float x) { return -log1pf(expf(-x)); }
; __device__ __forceinline__ void ret_unit(LAS unsigned char* lds, int u, const bf16* PROJ, const int* pos, const float* dec_f, const float* dec_b, const bf16* ST,
;                                          const float* gn_w, const float* gn_b, bf16* MIX, int tid, const WsRef& wsr) {
;     ...
;     const float lgf2 = log_sigmoid(dec_f[h]) * LOG2E, lgb2 = log_sigmoid(dec_b[h]) * LOG2E;
;     const u32x4* sfp = (const u32x4*)(ST + ((size_t)bh * 64 + c) * 16384); const u32x4* sbp = (const u32x4*)(ST + ((size_t)(8 + bh) * 64 + c) * 16384);
;     u32x4 sf[4], sb[4];
; #pragma unroll
;     for (int i = 0; i < 4; ++i) { sf[i] = sfp[tid + 512 * i]; sb[i] = sbp[tid + 512 * i]; }
;     u32x4 rq1[2], rq2[2], rk1[2], rk2[2], rv[4]; float rp[2];
; #pragma unroll
;     for (int ii = 0; ii < 2; ++ii) { const int it = tid + 512 * ii, dc = it & 7, j = it >> 3; const unsigned qo = (unsigned)WS_PROJ + (unsigned)(((unsigned)(row0 + j) * INC + h * 128 + dc * 8) * 2u);
;         rq1[ii] = ws_load16(wsr, qo); rq2[ii] = ws_load16(wsr, qo + 128u); rk1[ii] = ws_load16(wsr, qo + 1024u); rk2[ii] = ws_load16(wsr, qo + 1152u); rp[ii] = (float)pos[row0 + j]; }
	v_mul_f32_e32 v2, 0xbfb8aa3b, v1
	v_fma_f32 v3, v1, s41, -v2
	v_rndne_f32_e32 v4, v2
	v_fmac_f32_e32 v3, 0xb2a5705f, v1
	v_sub_f32_e32 v2, v2, v4
	v_add_f32_e32 v2, v2, v3
	v_exp_f32_e32 v2, v2
	v_cvt_i32_f32_e32 v3, v4
	v_cndmask_b32_e64 v0, v0, v17, s[68:69]
	v_cmp_nlt_f32_e64 s[68:69], s1, v1
	s_ashr_i32 s1, s0, 31
	v_ldexp_f32 v2, v2, v3
	v_cndmask_b32_e64 v2, 0, v2, s[68:69]
	v_cmp_ngt_f32_e64 s[68:69], s83, v1
	s_lshl_b64 s[0:1], s[0:1], 21
	s_add_u32 s0, s54, s0
	v_cndmask_b32_e64 v1, v228, v2, s[68:69]
	v_add_f32_e32 v4, 1.0, v1
	v_add_f32_e32 v2, -1.0, v4
	v_sub_f32_e32 v3, v2, v4
	v_add_f32_e32 v3, 1.0, v3
	v_sub_f32_e32 v2, v1, v2
	v_add_f32_e32 v5, v2, v3
	v_frexp_mant_f32_e32 v2, v4
	v_cmp_gt_f32_e64 s[68:69], s11, v2
	v_cvt_f64_f32_e32 v[2:3], v4
	v_frexp_exp_i32_f64_e32 v2, v[2:3]
	v_subbrev_co_u32_e64 v10, s[68:69], 0, v2, s[68:69]
	v_sub_u32_e32 v2, 0, v10
	v_ldexp_f32 v3, v4, v2
	v_add_f32_e32 v4, -1.0, v3
	v_add_f32_e32 v6, 1.0, v3
	v_ldexp_f32 v2, v5, v2
	v_add_f32_e32 v5, 1.0, v4
	v_add_f32_e32 v7, -1.0, v6
	v_sub_f32_e32 v5, v3, v5
	v_sub_f32_e32 v3, v3, v7
	v_add_f32_e32 v5, v2, v5
	v_add_f32_e32 v2, v2, v3
	v_add_f32_e32 v11, v6, v2
	v_rcp_f32_e32 v13, v11
	v_sub_f32_e32 v3, v6, v11
	v_add_f32_e32 v12, v2, v3
	v_add_f32_e32 v3, v4, v5
	v_mul_f32_e32 v15, v3, v13
	v_sub_f32_e32 v2, v4, v3
	v_mul_f32_e32 v4, v11, v15
	v_fma_f32 v6, v15, v11, -v4
	v_fmac_f32_e32 v6, v15, v12
	v_add_f32_e32 v14, v5, v2
	v_add_f32_e32 v2, v4, v6
	v_sub_f32_e32 v5, v3, v2
	v_pk_add_f32 v[8:9], v[2:3], v[4:5] neg_lo:[0,1] neg_hi:[0,1]
	v_mov_b32_e32 v7, v2
	v_pk_add_f32 v[2:3], v[8:9], v[6:7] neg_lo:[0,1] neg_hi:[0,1]
	v_cmp_neq_f32_e64 s[68:69], s88, v1
	v_add_f32_e32 v3, v14, v3
	v_add_f32_e32 v2, v2, v3
	v_add_f32_e32 v3, v5, v2
	v_mul_f32_e32 v14, v13, v3
	v_mul_f32_e32 v4, v11, v14
	v_fma_f32 v6, v14, v11, -v4
	v_fmac_f32_e32 v6, v14, v12
	v_sub_f32_e32 v5, v5, v3
	v_add_f32_e32 v11, v2, v5
	v_add_f32_e32 v2, v4, v6
	v_sub_f32_e32 v5, v3, v2
	v_pk_add_f32 v[8:9], v[2:3], v[4:5] neg_lo:[0,1] neg_hi:[0,1]
	v_mov_b32_e32 v7, v2
	v_pk_add_f32 v[2:3], v[8:9], v[6:7] neg_lo:[0,1] neg_hi:[0,1]
	s_addc_u32 s1, s55, s1
	v_add_f32_e32 v3, v11, v3
	v_add_f32_e32 v2, v2, v3
	v_add_f32_e32 v3, v15, v14
	v_add_f32_e32 v2, v5, v2
	v_sub_f32_e32 v4, v3, v15
	v_mul_f32_e32 v2, v13, v2
	v_sub_f32_e32 v4, v14, v4
	v_add_f32_e32 v4, v4, v2
	v_add_f32_e32 v6, v3, v4
	v_mul_f32_e32 v7, v6, v6
	v_fmamk_f32 v2, v7, 0x3e9b6dac, v223
	v_fmaak_f32 v105, v7, v2, 0x3f2aaada
	v_cvt_f32_i32_e32 v2, v10
	v_sub_f32_e32 v3, v6, v3
	v_sub_f32_e32 v3, v4, v3
	v_ldexp_f32 v8, v3, 1
	v_mul_f32_e32 v3, v6, v7
	v_ldexp_f32 v5, v6, 1
	v_pk_mul_f32 v[6:7], v[2:3], v[104:105]
	v_mul_f32_e32 v105, 0xbfb8aa3b, v0
	v_fma_f32 v4, v2, s33, -v6
	v_fmac_f32_e32 v4, 0xb102e308, v2
	v_pk_add_f32 v[2:3], v[6:7], v[4:5]
	s_mov_b32 s88, s84
	v_sub_f32_e32 v5, v3, v5
	v_sub_f32_e32 v5, v7, v5
	v_add_f32_e32 v9, v8, v5
	v_mov_b32_e32 v8, v6
	v_pk_add_f32 v[6:7], v[2:3], v[6:7] neg_lo:[0,1] neg_hi:[0,1]
	v_pk_add_f32 v[10:11], v[2:3], v[8:9]
	v_mov_b32_e32 v5, v2
	v_mov_b32_e32 v7, v11
	v_pk_add_f32 v[12:13], v[4:5], v[6:7] neg_lo:[0,1] neg_hi:[0,1]
	v_pk_add_f32 v[4:5], v[4:5], v[6:7]
	v_mov_b32_e32 v16, v3
	v_pk_add_f32 v[6:7], v[4:5], v[2:3] op_sel:[1,0] op_sel_hi:[0,1] neg_lo:[0,1] neg_hi:[0,1]
	v_pk_add_f32 v[14:15], v[10:11], v[6:7] op_sel_hi:[1,0] neg_lo:[0,1] neg_hi:[0,1]
	v_mov_b32_e32 v10, v11
	v_mov_b32_e32 v11, v5
	v_mov_b32_e32 v17, v6
	v_pk_add_f32 v[6:7], v[10:11], v[16:17] neg_lo:[0,1] neg_hi:[0,1]
	v_mov_b32_e32 v8, v9
	v_mov_b32_e32 v9, v2
	v_pk_add_f32 v[2:3], v[8:9], v[6:7] neg_lo:[0,1] neg_hi:[0,1]
	v_mov_b32_e32 v14, v12
	v_pk_add_f32 v[6:7], v[14:15], v[2:3]
	v_mov_b32_e32 v13, v5
	v_pk_add_f32 v[8:9], v[6:7], v[6:7] op_sel:[0,1] op_sel_hi:[1,0]
	s_nop 0
	v_pk_add_f32 v[4:5], v[4:5], v[8:9] op_sel:[1,0] op_sel_hi:[0,1]
	v_mov_b32_e32 v7, v4
	v_pk_add_f32 v[10:11], v[6:7], v[12:13] neg_lo:[0,1] neg_hi:[0,1]
	v_mov_b32_e32 v3, v8
	v_sub_f32_e32 v5, v6, v10
	v_pk_add_f32 v[2:3], v[2:3], v[10:11] neg_lo:[0,1] neg_hi:[0,1]
	v_sub_f32_e32 v5, v12, v5
	v_add_f32_e32 v2, v2, v5
	v_add_f32_e32 v2, v2, v3
	v_add_f32_e32 v2, v4, v2
	v_cndmask_b32_e64 v2, v228, v2, s[68:69]
	v_cmp_lt_f32_e64 s[68:69], |v1|, s8
	s_movk_i32 s8, 0x2000
	s_nop 0
	v_cndmask_b32_e64 v48, v2, v1, s[68:69]
	s_lshl_b32 s68, s82, 15
	s_add_u32 s0, s0, s68
	s_addc_u32 s1, s1, 0
	s_add_u32 s82, s0, 0x1000000
	v_lshl_add_u64 v[2:3], s[0:1], 0, v[96:97]
	s_addc_u32 s83, s1, 0
	v_add_co_u32_e64 v8, s[68:69], s8, v2
	v_lshl_add_u64 v[28:29], s[82:83], 0, v[96:97]
	s_nop 0
	v_addc_co_u32_e64 v9, s[68:69], 0, v3, s[68:69]
	v_add_co_u32_e64 v16, s[68:69], s8, v28
	global_load_dwordx4 v[4:7], v96, s[0:1]
	global_load_dwordx4 v[12:15], v96, s[82:83]
	v_addc_co_u32_e64 v17, s[68:69], 0, v29, s[68:69]
	global_load_dwordx4 v[8:11], v[8:9], off
	s_nop 0
	global_load_dwordx4 v[16:19], v[16:17], off
	s_nop 0
	global_load_dwordx4 v[24:27], v224, s[0:1]
	global_load_dwordx4 v[20:23], v224, s[82:83]
	s_movk_i32 s0, 0x6000
	v_add_co_u32_e64 v2, s[68:69], s0, v2
	s_lshl_b64 s[4:5], s[4:5], 13
	s_nop 0
	v_addc_co_u32_e64 v3, s[68:69], 0, v3, s[68:69]
	global_load_dwordx4 v[32:35], v[2:3], off
	v_add_co_u32_e64 v2, s[68:69], s0, v28
	s_or_b32 s4, s4, s81
	s_nop 0
	v_addc_co_u32_e64 v3, s[68:69], 0, v29, s[68:69]
	s_lshl_b32 s0, s80, 7
	v_or_b32_e32 v0, s4, v98
	global_load_dwordx4 v[36:39], v[2:3], off
	v_or_b32_e32 v2, s0, v106
	v_mul_lo_u32 v3, v0, s9
	v_mov_b32_e32 v1, s5
	v_or_b32_e32 v3, v3, v2
	v_lshl_add_u32 v3, v3, 1, v229
	v_lshl_add_u64 v[0:1], v[0:1], 2, s[12:13]
	buffer_load_dwordx4 v[50:53], v3, s[88:91], 0 offen
; __device__ __forceinline__ u32x4 ws_load16(const WsRef& w, unsigned byte_off) { return __builtin_bit_cast(u32x4, __builtin_amdgcn_raw_buffer_load_b128(w.r, byte_off, 0, 0)); }
; __device__ __forceinline__ float fexp2(float x) { return __builtin_amdgcn_exp2f(x); }
; __device__ __forceinline__ void ret_unit(LAS unsigned char* lds, int u, const bf16* PROJ, const int* pos, const float* dec_f, const float* dec_b, const bf16* ST,
;                                          const float* gn_w, const float* gn_b, bf16* MIX, int tid, const WsRef& wsr) {
;     ...
;     for (int ii = 0; ii < 2; ++ii) { const int it = tid + 512 * ii, dc = it & 7, j = it >> 3; const unsigned qo = (unsigned)WS_PROJ + (unsigned)(((unsigned)(row0 + j) * INC + h * 128 + dc * 8) * 2u);
;         rq1[ii] = ws_load16(wsr, qo); rq2[ii] = ws_load16(wsr, qo + 128u); rk1[ii] = ws_load16(wsr, qo + 1024u); rk2[ii] = ws_load16(wsr, qo + 1152u); rp[ii] = (float)pos[row0 + j]; }
; #pragma unroll
;     for (int ii = 0; ii < 2; ++ii) { const int it = tid + 512 * ii, dc = it & 7, j = it >> 3;
;         const u32x4 q1 = rq1[ii], q2 = rq2[ii], k1 = rk1[ii], k2 = rk2[ii];
;         const float p = rp[ii];
;         float sn[8], cs[8];
; #pragma unroll
;         for (int e = 0; e < 8; ++e) { const int i = dc * 8 + e; const float inv = fexp2(-(float)i * 0.20762050593046015f); fast_sincos(p * inv, sn[e], cs[e]); }
;     ...
;     for (int n = 0; n < 8; ++n) {
; #pragma unroll
;         for (int r = 0; r < 4; ++r) { const int key = n * 16 + 4 * fq + r; const int df = q - key; const float f = df >= 0 ? fexp2(lgf2 * (float)df) : fexp2(lgb2 * (float)(-df)); s[n][r] *= f; } }
	buffer_load_dwordx4 v[54:57], v3, s[88:91], 0 offen offset:128
	buffer_load_dwordx4 v[58:61], v3, s[88:91], 0 offen offset:1024
	buffer_load_dwordx4 v[62:65], v3, s[88:91], 0 offen offset:1152
	v_lshl_add_u64 v[66:67], s[4:5], 0, v[100:101]
	global_load_dword v0, v[0:1], off
	v_mul_f32_e32 v230, 0xbfb8aa3b, v48
	v_cndmask_b32_e64 v89, v105, v230, s[30:31]
	v_cndmask_b32_e64 v94, v105, v230, s[56:57]
	v_cndmask_b32_e64 v95, v105, v230, s[58:59]
	v_mul_f32_e32 v89, v89, v137
	v_cndmask_b32_e64 v92, v105, v230, s[74:75]
	v_cndmask_b32_e64 v93, v105, v230, s[76:77]
	v_mul_f32_e32 v94, v94, v142
	v_mul_f32_e32 v95, v95, v143
	v_exp_f32_e32 v89, v89
	v_mul_f32_e32 v92, v92, v140
	v_mul_f32_e32 v93, v93, v141
	v_exp_f32_e32 v94, v94
	v_exp_f32_e32 v95, v95
	v_exp_f32_e32 v92, v92
	v_exp_f32_e32 v93, v93
	v_cndmask_b32_e64 v130, v105, v230, s[60:61]
	v_cndmask_b32_e64 v131, v105, v230, s[62:63]
	v_cndmask_b32_e64 v48, v105, v230, s[42:43]
	v_mul_f32_e32 v130, v130, v144
	v_mul_f32_e32 v131, v131, v145
	v_mul_f32_e32 v48, v48, v127
	v_exp_f32_e32 v130, v130
	v_exp_f32_e32 v131, v131
	v_exp_f32_e32 v48, v48
	v_cndmask_b32_e64 v90, v105, v230, s[34:35]
	v_cndmask_b32_e64 v91, v105, v230, s[38:39]
	v_mul_f32_e32 v90, v90, v138
	v_mul_f32_e32 v91, v91, v139
	v_exp_f32_e32 v90, v90
	v_exp_f32_e32 v91, v91
	v_cndmask_b32_e64 v238, v105, v230, s[94:95]
	v_mul_f32_e32 v238, v238, v154
	v_exp_f32_e32 v238, v238
	v_cndmask_b32_e64 v234, v105, v230, s[78:79]
	v_cndmask_b32_e64 v235, v105, v230, s[2:3]
	v_cndmask_b32_e64 v236, v105, v230, s[92:93]
	v_cndmask_b32_e32 v237, v105, v230, vcc
	v_mul_f32_e32 v234, v234, v150
	v_mul_f32_e32 v235, v235, v151
	v_mul_f32_e32 v236, v236, v152
	v_mul_f32_e32 v237, v237, v153
	v_exp_f32_e32 v234, v234
	v_exp_f32_e32 v235, v235
	v_exp_f32_e32 v236, v236
	v_exp_f32_e32 v237, v237
	v_cndmask_b32_e64 v132, v105, v230, s[64:65]
	v_cndmask_b32_e64 v133, v105, v230, s[14:15]
	v_cndmask_b32_e64 v232, v105, v230, s[16:17]
	v_cndmask_b32_e64 v233, v105, v230, s[24:25]
	v_mul_f32_e32 v132, v132, v146
	v_mul_f32_e32 v133, v133, v147
	v_mul_f32_e32 v232, v232, v148
	v_mul_f32_e32 v233, v233, v149
	v_exp_f32_e32 v132, v132
	v_exp_f32_e32 v133, v133
	v_exp_f32_e32 v232, v232
	v_exp_f32_e32 v233, v233
	s_mov_b32 s1, 0x800000
	s_add_i32 s73, s73, s40
	s_cmpk_lt_i32 s73, 0x200
	s_waitcnt vmcnt(4)
	v_lshlrev_b32_e32 v82, 16, v50
	s_waitcnt vmcnt(3)
	v_lshlrev_b32_e32 v84, 16, v54
	v_and_b32_e32 v85, 0xffff0000, v54
	v_and_b32_e32 v83, 0xffff0000, v50
	s_waitcnt vmcnt(0)
	v_cvt_f32_i32_e32 v49, v0
	v_mul_lo_u32 v0, v66, s9
	v_or_b32_e32 v0, v0, v2
	v_lshl_add_u32 v0, v0, 1, v229
	v_lshl_add_u64 v[66:67], v[66:67], 2, s[12:13]
	buffer_load_dwordx4 v[44:47], v0, s[88:91], 0 offen
	buffer_load_dwordx4 v[40:43], v0, s[88:91], 0 offen offset:128
	buffer_load_dwordx4 v[28:31], v0, s[88:91], 0 offen offset:1024
	s_nop 0
	buffer_load_dwordx4 v[0:3], v0, s[88:91], 0 offen offset:1152
	v_mul_f32_e32 v70, v109, v49
	global_load_dword v66, v[66:67], off
	v_mul_f32_e32 v71, 0.15915494, v70
	v_rndne_f32_e32 v71, v71
	v_fmac_f32_e32 v70, 0xc0c90000, v71
	v_fmac_f32_e32 v70, 0xbafdaa22, v71
	v_mul_f32_e32 v71, 0.15915494, v70
	v_sin_f32_e32 v70, v71
	v_cos_f32_e32 v72, v71
	v_mul_f32_e32 v71, v110, v49
	v_mul_f32_e32 v73, 0.15915494, v71
	v_mul_f32_e32 v74, v111, v49
	v_rndne_f32_e32 v73, v73
	v_mul_f32_e32 v75, 0.15915494, v74
	v_fmac_f32_e32 v71, 0xc0c90000, v73
	v_rndne_f32_e32 v75, v75
	v_fmac_f32_e32 v71, 0xbafdaa22, v73
	v_fmac_f32_e32 v74, 0xc0c90000, v75
	v_mul_f32_e32 v73, 0.15915494, v71
	v_fmac_f32_e32 v74, 0xbafdaa22, v75
	v_sin_f32_e32 v71, v73
	v_mul_f32_e32 v75, 0.15915494, v74
	v_cos_f32_e32 v73, v73
	v_sin_f32_e32 v74, v75
	v_cos_f32_e32 v76, v75
	v_mul_f32_e32 v75, v112, v49
	v_mul_f32_e32 v77, 0.15915494, v75
	v_rndne_f32_e32 v77, v77
	v_mul_f32_e32 v78, v113, v49
	v_fmac_f32_e32 v75, 0xc0c90000, v77
	v_mul_f32_e32 v79, 0.15915494, v78
	v_fmac_f32_e32 v75, 0xbafdaa22, v77
	v_rndne_f32_e32 v79, v79
	v_mul_f32_e32 v77, 0.15915494, v75
	v_fmac_f32_e32 v78, 0xc0c90000, v79
	v_sin_f32_e32 v75, v77
	v_fmac_f32_e32 v78, 0xbafdaa22, v79
	v_cos_f32_e32 v77, v77
	v_mul_f32_e32 v79, 0.15915494, v78
	v_sin_f32_e32 v78, v79
	v_cos_f32_e32 v80, v79
	s_waitcnt vmcnt(0)
; #define LAS __attribute__((address_space(3)))
; __device__ __forceinline__ unsigned pk2(float lo, float hi) { return pg8::cvt_pk_bf16(lo, hi); }
; __device__ __forceinline__ float bflo(unsigned w) { return __uint_as_float(w << 16); }
; __device__ __forceinline__ float bfhi(unsigned w) { return __uint_as_float(w & 0xffff0000u); }
; __device__ __forceinline__ float fexp2(float x) { return __builtin_amdgcn_exp2f(x); }
; __device__ __forceinline__ void ret_unit(LAS unsigned char* lds, int u, const bf16* PROJ, const int* pos, const float* dec_f, const float* dec_b, const bf16* ST,
;                                          const float* gn_w, const float* gn_b, bf16* MIX, int tid, const WsRef& wsr) {
;     ...
;     for (int ii = 0; ii < 2; ++ii) { const int it = tid + 512 * ii, dc = it & 7, j = it >> 3;
;         const u32x4 q1 = rq1[ii], q2 = rq2[ii], k1 = rk1[ii], k2 = rk2[ii];
;         const float p = rp[ii];
;         float sn[8], cs[8];
; #pragma unroll
;         for (int e = 0; e < 8; ++e) { const int i = dc * 8 + e; const float inv = fexp2(-(float)i * 0.20762050593046015f); fast_sincos(p * inv, sn[e], cs[e]); }
;         u32x4 oq1, oq2, ok1, ok2;
; #pragma unroll
;         for (int e = 0; e < 4; ++e) { const int e0 = 2 * e, e1 = 2 * e + 1;
;             const float a0 = bflo(q1[e]), a1 = bfhi(q1[e]), b0 = bflo(q2[e]), b1 = bfhi(q2[e]);
;             oq1[e] = pk2(a0 * cs[e0] - b0 * sn[e0], a1 * cs[e1] - b1 * sn[e1]); oq2[e] = pk2(b0 * cs[e0] + a0 * sn[e0], b1 * cs[e1] + a1 * sn[e1]);
;             const float c0 = bflo(k1[e]) * 0.08838834764831845f, c1 = bfhi(k1[e]) * 0.08838834764831845f, d0 = bflo(k2[e]) * 0.08838834764831845f, d1 = bfhi(k2[e]) * 0.08838834764831845f;
;             ok1[e] = pk2(c0 * cs[e0] - d0 * sn[e0], c1 * cs[e1] - d1 * sn[e1]); ok2[e] = pk2(d0 * cs[e0] + c0 * sn[e0], d1 * cs[e1] + c1 * sn[e1]); }
;         *(LAS u32x4*)(Qs + j * LDT + dc * 8) = oq1; *(LAS u32x4*)(Qs + j * LDT + 64 + dc * 8) = oq2;
;         *(LAS u32x4*)(Ks + j * LDT + dc * 8) = ok1; *(LAS u32x4*)(Ks + j * LDT + 64 + dc * 8) = ok2; }
	v_cvt_f32_i32_e32 v88, v66
	v_mul_f32_e32 v66, v107, v49
	v_mul_f32_e32 v67, 0.15915494, v66
	v_rndne_f32_e32 v67, v67
	v_fmac_f32_e32 v66, 0xc0c90000, v67
	v_fmac_f32_e32 v66, 0xbafdaa22, v67
	v_mul_f32_e32 v67, 0.15915494, v66
	v_sin_f32_e32 v66, v67
	v_cos_f32_e32 v68, v67
	v_mul_f32_e32 v67, v108, v49
	v_mul_f32_e32 v69, 0.15915494, v67
	v_rndne_f32_e32 v69, v69
	v_fmac_f32_e32 v67, 0xc0c90000, v69
	v_fmac_f32_e32 v67, 0xbafdaa22, v69
	v_mul_f32_e32 v69, 0.15915494, v67
	v_sin_f32_e32 v67, v69
	v_cos_f32_e32 v69, v69
	v_mul_f32_e32 v49, v114, v49
	v_mul_f32_e32 v79, 0.15915494, v49
	v_pk_mul_f32 v[86:87], v[66:67], v[84:85]
	v_rndne_f32_e32 v79, v79
	v_pk_fma_f32 v[86:87], v[68:69], v[82:83], v[86:87] neg_lo:[0,0,1] neg_hi:[0,0,1]
	v_pk_mul_f32 v[82:83], v[66:67], v[82:83]
	v_cvt_pk_bf16_f32 v50, v86, v87
	v_pk_fma_f32 v[82:83], v[68:69], v[84:85], v[82:83]
	v_lshlrev_b32_e32 v84, 16, v62
	v_cvt_pk_bf16_f32 v54, v82, v83
	v_lshlrev_b32_e32 v82, 16, v58
	v_and_b32_e32 v83, 0xffff0000, v58
	v_and_b32_e32 v85, 0xffff0000, v62
	v_pk_mul_f32 v[82:83], v[82:83], s[10:11] op_sel_hi:[1,0]
	v_pk_mul_f32 v[84:85], v[84:85], s[10:11] op_sel_hi:[1,0]
	v_fmac_f32_e32 v49, 0xc0c90000, v79
	v_pk_mul_f32 v[86:87], v[84:85], v[66:67]
	v_pk_mul_f32 v[66:67], v[82:83], v[66:67]
	v_pk_fma_f32 v[86:87], v[82:83], v[68:69], v[86:87] neg_lo:[0,0,1] neg_hi:[0,0,1]
	v_pk_fma_f32 v[66:67], v[84:85], v[68:69], v[66:67]
	v_lshlrev_b32_e32 v68, 16, v55
	v_and_b32_e32 v69, 0xffff0000, v55
	v_cvt_pk_bf16_f32 v62, v66, v67
	v_lshlrev_b32_e32 v66, 16, v51
	v_and_b32_e32 v67, 0xffff0000, v51
	v_pk_mul_f32 v[82:83], v[70:71], v[68:69]
	v_fmac_f32_e32 v49, 0xbafdaa22, v79
	v_pk_fma_f32 v[82:83], v[72:73], v[66:67], v[82:83] neg_lo:[0,0,1] neg_hi:[0,0,1]
	v_pk_mul_f32 v[66:67], v[70:71], v[66:67]
	v_cvt_pk_bf16_f32 v51, v82, v83
	v_pk_fma_f32 v[66:67], v[72:73], v[68:69], v[66:67]
	v_lshlrev_b32_e32 v68, 16, v63
	v_and_b32_e32 v69, 0xffff0000, v63
	v_cvt_pk_bf16_f32 v55, v66, v67
	v_lshlrev_b32_e32 v66, 16, v59
	v_and_b32_e32 v67, 0xffff0000, v59
	v_pk_mul_f32 v[68:69], v[68:69], s[10:11] op_sel_hi:[1,0]
	v_pk_mul_f32 v[66:67], v[66:67], s[10:11] op_sel_hi:[1,0]
	v_pk_mul_f32 v[82:83], v[68:69], v[70:71]
	v_mul_f32_e32 v49, 0.15915494, v49
	v_pk_fma_f32 v[82:83], v[66:67], v[72:73], v[82:83] neg_lo:[0,0,1] neg_hi:[0,0,1]
	v_pk_mul_f32 v[66:67], v[66:67], v[70:71]
	v_sin_f32_e32 v79, v49
	v_pk_fma_f32 v[66:67], v[68:69], v[72:73], v[66:67]
	v_lshlrev_b32_e32 v68, 16, v56
	v_and_b32_e32 v69, 0xffff0000, v56
	v_cvt_pk_bf16_f32 v63, v66, v67
	v_lshlrev_b32_e32 v66, 16, v52
	v_and_b32_e32 v67, 0xffff0000, v52
	v_pk_mul_f32 v[70:71], v[74:75], v[68:69]
	v_cos_f32_e32 v81, v49
	v_pk_fma_f32 v[70:71], v[76:77], v[66:67], v[70:71] neg_lo:[0,0,1] neg_hi:[0,0,1]
	v_pk_mul_f32 v[66:67], v[74:75], v[66:67]
	v_cvt_pk_bf16_f32 v52, v70, v71
	v_pk_fma_f32 v[66:67], v[76:77], v[68:69], v[66:67]
	v_lshlrev_b32_e32 v68, 16, v64
	v_and_b32_e32 v69, 0xffff0000, v64
	v_cvt_pk_bf16_f32 v56, v66, v67
	v_lshlrev_b32_e32 v66, 16, v60
	v_and_b32_e32 v67, 0xffff0000, v60
	v_pk_mul_f32 v[68:69], v[68:69], s[10:11] op_sel_hi:[1,0]
	v_pk_mul_f32 v[66:67], v[66:67], s[10:11] op_sel_hi:[1,0]
	v_pk_mul_f32 v[70:71], v[68:69], v[74:75]
	v_mul_f32_e32 v49, v107, v88
	v_pk_fma_f32 v[70:71], v[66:67], v[76:77], v[70:71] neg_lo:[0,0,1] neg_hi:[0,0,1]
	v_pk_mul_f32 v[66:67], v[66:67], v[74:75]
	v_cvt_pk_bf16_f32 v60, v70, v71
	v_pk_fma_f32 v[66:67], v[68:69], v[76:77], v[66:67]
	v_lshlrev_b32_e32 v68, 16, v57
	v_and_b32_e32 v69, 0xffff0000, v57
	v_cvt_pk_bf16_f32 v64, v66, v67
	v_lshlrev_b32_e32 v66, 16, v53
	v_and_b32_e32 v67, 0xffff0000, v53
	v_pk_mul_f32 v[70:71], v[78:79], v[68:69]
	v_cvt_pk_bf16_f32 v58, v86, v87
	v_pk_fma_f32 v[70:71], v[80:81], v[66:67], v[70:71] neg_lo:[0,0,1] neg_hi:[0,0,1]
	v_pk_mul_f32 v[66:67], v[78:79], v[66:67]
	v_cvt_pk_bf16_f32 v53, v70, v71
	v_pk_fma_f32 v[66:67], v[80:81], v[68:69], v[66:67]
	v_lshlrev_b32_e32 v68, 16, v65
	v_and_b32_e32 v69, 0xffff0000, v65
	v_cvt_pk_bf16_f32 v57, v66, v67
	v_lshlrev_b32_e32 v66, 16, v61
	v_and_b32_e32 v67, 0xffff0000, v61
	v_pk_mul_f32 v[68:69], v[68:69], s[10:11] op_sel_hi:[1,0]
	v_pk_mul_f32 v[66:67], v[66:67], s[10:11] op_sel_hi:[1,0]
	v_pk_mul_f32 v[70:71], v[68:69], v[78:79]
	v_cvt_pk_bf16_f32 v59, v82, v83
	v_pk_fma_f32 v[70:71], v[66:67], v[80:81], v[70:71] neg_lo:[0,0,1] neg_hi:[0,0,1]
	v_pk_mul_f32 v[66:67], v[66:67], v[78:79]
	v_cvt_pk_bf16_f32 v61, v70, v71
	v_pk_fma_f32 v[66:67], v[68:69], v[80:81], v[66:67]
	v_lshlrev_b32_e32 v68, 16, v40
	v_cvt_pk_bf16_f32 v65, v66, v67
	ds_write_b128 v115, v[50:53]
	ds_write_b128 v115, v[54:57] offset:128
	ds_write_b128 v115, v[58:61] offset:34816
	ds_write_b128 v115, v[62:65] offset:34944
	v_mul_f32_e32 v50, 0.15915494, v49
	v_rndne_f32_e32 v50, v50
	v_fmac_f32_e32 v49, 0xc0c90000, v50
	v_fmac_f32_e32 v49, 0xbafdaa22, v50
	v_mul_f32_e32 v49, 0.15915494, v49
	v_sin_f32_e32 v50, v49
	v_cos_f32_e32 v52, v49
	v_mul_f32_e32 v49, v108, v88
	v_mul_f32_e32 v51, 0.15915494, v49
	v_rndne_f32_e32 v51, v51
	v_fmac_f32_e32 v49, 0xc0c90000, v51
	v_fmac_f32_e32 v49, 0xbafdaa22, v51
	v_mul_f32_e32 v49, 0.15915494, v49
	v_sin_f32_e32 v51, v49
	v_cos_f32_e32 v53, v49
	v_mul_f32_e32 v49, v109, v88
	v_mul_f32_e32 v54, 0.15915494, v49
	v_rndne_f32_e32 v54, v54
	v_fmac_f32_e32 v49, 0xc0c90000, v54
	v_fmac_f32_e32 v49, 0xbafdaa22, v54
	v_mul_f32_e32 v49, 0.15915494, v49
	v_sin_f32_e32 v54, v49
	v_cos_f32_e32 v56, v49
	v_mul_f32_e32 v49, v110, v88
	v_mul_f32_e32 v55, 0.15915494, v49
	v_rndne_f32_e32 v55, v55
	v_fmac_f32_e32 v49, 0xc0c90000, v55
	v_fmac_f32_e32 v49, 0xbafdaa22, v55
	v_mul_f32_e32 v49, 0.15915494, v49
; #define LAS __attribute__((address_space(3)))
; __device__ __forceinline__ unsigned pk2(float lo, float hi) { return pg8::cvt_pk_bf16(lo, hi); }
; __device__ __forceinline__ float bflo(unsigned w) { return __uint_as_float(w << 16); }
; __device__ __forceinline__ float bfhi(unsigned w) { return __uint_as_float(w & 0xffff0000u); }
; __device__ __forceinline__ u32x4 ws_load16(const WsRef& w, unsigned byte_off) { return __builtin_bit_cast(u32x4, __builtin_amdgcn_raw_buffer_load_b128(w.r, byte_off, 0, 0)); }
; __device__ __forceinline__ void ret_unit(LAS unsigned char* lds, int u, const bf16* PROJ, const int* pos, const float* dec_f, const float* dec_b, const bf16* ST,
;                                          const float* gn_w, const float* gn_b, bf16* MIX, int tid, const WsRef& wsr) {
;     ...
;     for (int ii = 0; ii < 2; ++ii) { const int it = tid + 512 * ii, dc = it & 7, j = it >> 3;
;         const u32x4 q1 = rq1[ii], q2 = rq2[ii], k1 = rk1[ii], k2 = rk2[ii];
;         const float p = rp[ii];
;         float sn[8], cs[8];
; #pragma unroll
;         for (int e = 0; e < 8; ++e) { const int i = dc * 8 + e; const float inv = fexp2(-(float)i * 0.20762050593046015f); fast_sincos(p * inv, sn[e], cs[e]); }
;         u32x4 oq1, oq2, ok1, ok2;
; #pragma unroll
;         for (int e = 0; e < 4; ++e) { const int e0 = 2 * e, e1 = 2 * e + 1;
;             const float a0 = bflo(q1[e]), a1 = bfhi(q1[e]), b0 = bflo(q2[e]), b1 = bfhi(q2[e]);
;             oq1[e] = pk2(a0 * cs[e0] - b0 * sn[e0], a1 * cs[e1] - b1 * sn[e1]); oq2[e] = pk2(b0 * cs[e0] + a0 * sn[e0], b1 * cs[e1] + a1 * sn[e1]);
;             const float c0 = bflo(k1[e]) * 0.08838834764831845f, c1 = bfhi(k1[e]) * 0.08838834764831845f, d0 = bflo(k2[e]) * 0.08838834764831845f, d1 = bfhi(k2[e]) * 0.08838834764831845f;
;             ok1[e] = pk2(c0 * cs[e0] - d0 * sn[e0], c1 * cs[e1] - d1 * sn[e1]); ok2[e] = pk2(d0 * cs[e0] + c0 * sn[e0], d1 * cs[e1] + c1 * sn[e1]); }
;         *(LAS u32x4*)(Qs + j * LDT + dc * 8) = oq1; *(LAS u32x4*)(Qs + j * LDT + 64 + dc * 8) = oq2;
;         *(LAS u32x4*)(Ks + j * LDT + dc * 8) = ok1; *(LAS u32x4*)(Ks + j * LDT + 64 + dc * 8) = ok2; }
; #pragma unroll
;     for (int ii = 0; ii < 4; ++ii) { const int it = tid + 512 * ii, ec = it & 15, j = it >> 4; rv[ii] = ws_load16(wsr, (unsigned)WS_PROJ + (unsigned)(((unsigned)(row0 + j) * INC + 1024 + h * 128 + ec * 8) * 2u)); }
	v_sin_f32_e32 v55, v49
	v_cos_f32_e32 v57, v49
	v_mul_f32_e32 v49, v111, v88
	v_mul_f32_e32 v58, 0.15915494, v49
	v_rndne_f32_e32 v58, v58
	v_fmac_f32_e32 v49, 0xc0c90000, v58
	v_fmac_f32_e32 v49, 0xbafdaa22, v58
	v_mul_f32_e32 v49, 0.15915494, v49
	v_sin_f32_e32 v58, v49
	v_cos_f32_e32 v60, v49
	v_mul_f32_e32 v49, v112, v88
	v_and_b32_e32 v69, 0xffff0000, v40
	v_mul_f32_e32 v59, 0.15915494, v49
	v_lshlrev_b32_e32 v66, 16, v44
	v_and_b32_e32 v67, 0xffff0000, v44
	v_pk_mul_f32 v[70:71], v[50:51], v[68:69]
	v_rndne_f32_e32 v59, v59
	v_pk_fma_f32 v[70:71], v[52:53], v[66:67], v[70:71] neg_lo:[0,0,1] neg_hi:[0,0,1]
	v_pk_mul_f32 v[66:67], v[50:51], v[66:67]
	v_fmac_f32_e32 v49, 0xc0c90000, v59
	v_pk_fma_f32 v[66:67], v[52:53], v[68:69], v[66:67]
	v_fmac_f32_e32 v49, 0xbafdaa22, v59
	v_cvt_pk_bf16_f32 v44, v66, v67
	v_lshlrev_b32_e32 v66, 16, v28
	v_and_b32_e32 v67, 0xffff0000, v28
	v_lshlrev_b32_e32 v68, 16, v0
	v_and_b32_e32 v69, 0xffff0000, v0
	v_mul_f32_e32 v49, 0.15915494, v49
	v_pk_mul_f32 v[66:67], v[66:67], s[10:11] op_sel_hi:[1,0]
	v_pk_mul_f32 v[68:69], v[68:69], s[10:11] op_sel_hi:[1,0]
	v_sin_f32_e32 v59, v49
	v_cos_f32_e32 v61, v49
	v_mul_f32_e32 v49, v113, v88
	v_cvt_pk_bf16_f32 v40, v70, v71
	v_pk_mul_f32 v[70:71], v[68:69], v[50:51]
	v_pk_mul_f32 v[50:51], v[66:67], v[50:51]
	v_mul_f32_e32 v62, 0.15915494, v49
	v_pk_fma_f32 v[70:71], v[66:67], v[52:53], v[70:71] neg_lo:[0,0,1] neg_hi:[0,0,1]
	v_pk_fma_f32 v[50:51], v[68:69], v[52:53], v[50:51]
	v_lshlrev_b32_e32 v52, 16, v41
	v_and_b32_e32 v53, 0xffff0000, v41
	v_rndne_f32_e32 v62, v62
	v_cvt_pk_bf16_f32 v28, v50, v51
	v_lshlrev_b32_e32 v50, 16, v45
	v_and_b32_e32 v51, 0xffff0000, v45
	v_pk_mul_f32 v[66:67], v[54:55], v[52:53]
	v_fmac_f32_e32 v49, 0xc0c90000, v62
	v_pk_fma_f32 v[66:67], v[56:57], v[50:51], v[66:67] neg_lo:[0,0,1] neg_hi:[0,0,1]
	v_pk_mul_f32 v[50:51], v[54:55], v[50:51]
	v_fmac_f32_e32 v49, 0xbafdaa22, v62
	v_pk_fma_f32 v[50:51], v[56:57], v[52:53], v[50:51]
	v_lshlrev_b32_e32 v52, 16, v1
	v_and_b32_e32 v53, 0xffff0000, v1
	v_mul_f32_e32 v49, 0.15915494, v49
	v_cvt_pk_bf16_f32 v45, v50, v51
	v_lshlrev_b32_e32 v50, 16, v29
	v_and_b32_e32 v51, 0xffff0000, v29
	v_pk_mul_f32 v[52:53], v[52:53], s[10:11] op_sel_hi:[1,0]
	v_sin_f32_e32 v62, v49
	v_cos_f32_e32 v64, v49
	v_mul_f32_e32 v49, v114, v88
	v_cvt_pk_bf16_f32 v41, v66, v67
	v_pk_mul_f32 v[50:51], v[50:51], s[10:11] op_sel_hi:[1,0]
	v_pk_mul_f32 v[66:67], v[52:53], v[54:55]
	v_mul_f32_e32 v63, 0.15915494, v49
	v_pk_fma_f32 v[66:67], v[50:51], v[56:57], v[66:67] neg_lo:[0,0,1] neg_hi:[0,0,1]
	v_pk_mul_f32 v[50:51], v[50:51], v[54:55]
	v_rndne_f32_e32 v63, v63
	v_pk_fma_f32 v[50:51], v[52:53], v[56:57], v[50:51]
	v_lshlrev_b32_e32 v52, 16, v42
	v_and_b32_e32 v53, 0xffff0000, v42
	v_fmac_f32_e32 v49, 0xc0c90000, v63
	v_cvt_pk_bf16_f32 v29, v50, v51
	v_lshlrev_b32_e32 v50, 16, v46
	v_and_b32_e32 v51, 0xffff0000, v46
	v_pk_mul_f32 v[54:55], v[58:59], v[52:53]
	v_fmac_f32_e32 v49, 0xbafdaa22, v63
	v_pk_fma_f32 v[54:55], v[60:61], v[50:51], v[54:55] neg_lo:[0,0,1] neg_hi:[0,0,1]
	v_pk_mul_f32 v[50:51], v[58:59], v[50:51]
	v_mul_f32_e32 v49, 0.15915494, v49
	v_pk_fma_f32 v[50:51], v[60:61], v[52:53], v[50:51]
	v_lshlrev_b32_e32 v52, 16, v2
	v_and_b32_e32 v53, 0xffff0000, v2
	v_sin_f32_e32 v63, v49
	v_cvt_pk_bf16_f32 v46, v50, v51
	v_lshlrev_b32_e32 v50, 16, v30
	v_and_b32_e32 v51, 0xffff0000, v30
	v_pk_mul_f32 v[52:53], v[52:53], s[10:11] op_sel_hi:[1,0]
	v_cos_f32_e32 v65, v49
	v_cvt_pk_bf16_f32 v42, v54, v55
	v_pk_mul_f32 v[50:51], v[50:51], s[10:11] op_sel_hi:[1,0]
	v_pk_mul_f32 v[54:55], v[52:53], v[58:59]
	v_cvt_pk_bf16_f32 v0, v70, v71
	v_pk_fma_f32 v[54:55], v[50:51], v[60:61], v[54:55] neg_lo:[0,0,1] neg_hi:[0,0,1]
	v_pk_mul_f32 v[50:51], v[50:51], v[58:59]
	v_cvt_pk_bf16_f32 v2, v54, v55
	v_pk_fma_f32 v[50:51], v[52:53], v[60:61], v[50:51]
	v_lshlrev_b32_e32 v52, 16, v43
	v_and_b32_e32 v53, 0xffff0000, v43
	v_cvt_pk_bf16_f32 v30, v50, v51
	v_lshlrev_b32_e32 v50, 16, v47
	v_and_b32_e32 v51, 0xffff0000, v47
	v_pk_mul_f32 v[54:55], v[62:63], v[52:53]
	v_cvt_pk_bf16_f32 v1, v66, v67
	v_pk_fma_f32 v[54:55], v[64:65], v[50:51], v[54:55] neg_lo:[0,0,1] neg_hi:[0,0,1]
	v_pk_mul_f32 v[50:51], v[62:63], v[50:51]
	v_cvt_pk_bf16_f32 v43, v54, v55
	v_pk_fma_f32 v[50:51], v[64:65], v[52:53], v[50:51]
	v_lshlrev_b32_e32 v52, 16, v3
	v_and_b32_e32 v53, 0xffff0000, v3
	v_cvt_pk_bf16_f32 v47, v50, v51
	v_lshlrev_b32_e32 v50, 16, v31
	v_and_b32_e32 v51, 0xffff0000, v31
	v_pk_mul_f32 v[52:53], v[52:53], s[10:11] op_sel_hi:[1,0]
	v_pk_mul_f32 v[50:51], v[50:51], s[10:11] op_sel_hi:[1,0]
	v_pk_mul_f32 v[54:55], v[52:53], v[62:63]
	v_add_u32_e32 v49, v124, v125
	v_pk_fma_f32 v[54:55], v[50:51], v[64:65], v[54:55] neg_lo:[0,0,1] neg_hi:[0,0,1]
	v_pk_mul_f32 v[50:51], v[50:51], v[62:63]
	v_cvt_pk_bf16_f32 v3, v54, v55
	v_pk_fma_f32 v[50:51], v[52:53], v[64:65], v[50:51]
	v_cndmask_b32_e64 v86, v105, v230, s[66:67]
	v_cvt_pk_bf16_f32 v31, v50, v51
	ds_write_b128 v116, v[40:43]
	ds_write_b128 v116, v[44:47] offset:128
	ds_write_b128 v116, v[0:3] offset:34816
	ds_write_b128 v116, v[28:31] offset:34944
	v_or_b32_e32 v44, s0, v222
	v_or_b32_e32 v0, s4, v99
	v_mad_u64_u32 v[0:1], s[68:69], v0, s9, v[44:45]
	v_lshl_add_u32 v0, v0, 1, v229
	buffer_load_dwordx4 v[0:3], v0, s[88:91], 0 offen
	v_or_b32_e32 v28, s4, v117
	v_mad_u64_u32 v[28:29], s[68:69], v28, s9, v[44:45]
	v_lshl_add_u32 v28, v28, 1, v229
	buffer_load_dwordx4 v[28:31], v28, s[88:91], 0 offen
	v_or_b32_e32 v40, s4, v118
	v_mad_u64_u32 v[40:41], s[68:69], v40, s9, v[44:45]
	v_lshl_add_u32 v40, v40, 1, v229
	buffer_load_dwordx4 v[40:43], v40, s[88:91], 0 offen
	v_add_u32_e32 v45, s4, v119
	v_mad_u64_u32 v[44:45], s[68:69], v45, s9, v[44:45]
	v_lshl_add_u32 v44, v44, 1, v229
	buffer_load_dwordx4 v[44:47], v44, s[88:91], 0 offen
	s_waitcnt vmcnt(3)
; #define LAS __attribute__((address_space(3)))
; __device__ __forceinline__ float fexp2(float x) { return __builtin_amdgcn_exp2f(x); }
; #define MFMA16(a, b, c) __builtin_amdgcn_mfma_f32_16x16x32_bf16((a), (b), (c), 0, 0, 0)
; __device__ __forceinline__ void ret_unit(LAS unsigned char* lds, int u, const bf16* PROJ, const int* pos, const float* dec_f, const float* dec_b, const bf16* ST,
;                                          const float* gn_w, const float* gn_b, bf16* MIX, int tid, const WsRef& wsr) {
;     ...
;     for (int ii = 0; ii < 4; ++ii) { const int it = tid + 512 * ii, ec = it & 15, j = it >> 4; const u32x4 w = rv[ii];
;         const int jsw = (((j >> 3) ^ (ec & 7)) << 3) | (j & 7);
; #pragma unroll
;         for (int e = 0; e < 4; ++e) { VT[(ec * 8 + 2 * e) * LDT + jsw] = (bf16)(w[e] & 0xffffu); VT[(ec * 8 + 2 * e + 1) * LDT + jsw] = (bf16)(w[e] >> 16); } }
;     __syncthreads();
;     const int q = wave * 16 + fr;
;     bf16x8 qf[4];
; #pragma unroll
;     for (int kk = 0; kk < 4; ++kk) qf[kk] = *(const LAS bf16x8*)(Qs + q * LDT + kk * 32 + fq * 8);
;     f32x4 s[8];
; #pragma unroll
;     for (int n = 0; n < 8; ++n) s[n] = (f32x4){0.f, 0.f, 0.f, 0.f};
; #pragma unroll
;     for (int kk = 0; kk < 4; ++kk)
; #pragma unroll
;         for (int n = 0; n < 8; ++n) { const bf16x8 kf = *(const LAS bf16x8*)(Ks + (n * 16 + fr) * LDT + kk * 32 + fq * 8); s[n] = MFMA16(kf, qf[kk], s[n]); }
;     ...
;     for (int n = 0; n < 8; ++n) {
; #pragma unroll
;         for (int r = 0; r < 4; ++r) { const int key = n * 16 + 4 * fq + r; const int df = q - key; const float f = df >= 0 ? fexp2(lgf2 * (float)df) : fexp2(lgb2 * (float)(-df)); s[n][r] *= f; } }
	ds_write_b16 v120, v0
	ds_write_b16_d16_hi v120, v0 offset:272
	ds_write_b16 v120, v1 offset:544
	ds_write_b16_d16_hi v120, v1 offset:816
	ds_write_b16 v120, v2 offset:1088
	ds_write_b16_d16_hi v120, v2 offset:1360
	ds_write_b16 v120, v3 offset:1632
	ds_write_b16_d16_hi v120, v3 offset:1904
	s_waitcnt vmcnt(2)
	ds_write_b16 v121, v28
	ds_write_b16_d16_hi v121, v28 offset:272
	ds_write_b16 v121, v29 offset:544
	ds_write_b16_d16_hi v121, v29 offset:816
	ds_write_b16 v121, v30 offset:1088
	ds_write_b16_d16_hi v121, v30 offset:1360
	ds_write_b16 v121, v31 offset:1632
	ds_write_b16_d16_hi v121, v31 offset:1904
	s_waitcnt vmcnt(1)
	ds_write_b16 v122, v40
	ds_write_b16_d16_hi v122, v40 offset:272
	ds_write_b16 v122, v41 offset:544
	ds_write_b16_d16_hi v122, v41 offset:816
	ds_write_b16 v122, v42 offset:1088
	ds_write_b16_d16_hi v122, v42 offset:1360
	ds_write_b16 v122, v43 offset:1632
	ds_write_b16_d16_hi v122, v43 offset:1904
	s_waitcnt vmcnt(0)
	ds_write_b16 v123, v44
	ds_write_b16_d16_hi v123, v44 offset:272
	ds_write_b16 v123, v45 offset:544
	ds_write_b16_d16_hi v123, v45 offset:816
	ds_write_b16 v123, v46 offset:1088
	ds_write_b16_d16_hi v123, v46 offset:1360
	ds_write_b16 v123, v47 offset:1632
	ds_write_b16_d16_hi v123, v47 offset:1904
	s_waitcnt lgkmcnt(0)
	s_barrier
	ds_read_b128 v[44:47], v225
	ds_read_b128 v[40:43], v225 offset:64
	ds_read_b128 v[28:31], v225 offset:128
	ds_read_b128 v[0:3], v225 offset:192
	ds_read_b128 v[50:53], v226 offset:34816
	ds_read_b128 v[54:57], v226 offset:39168
	ds_read_b128 v[82:85], v226 offset:34880
	s_waitcnt lgkmcnt(2)
	v_mfma_f32_16x16x32_bf16 v[50:53], v[50:53], v[44:47], 0
	ds_read_b128 v[58:61], v226 offset:43520
	ds_read_b128 v[62:65], v226 offset:47872
	ds_read_b128 v[66:69], v226 offset:52224
	s_waitcnt lgkmcnt(3)
	v_mfma_f32_16x16x32_bf16 v[50:53], v[82:85], v[40:43], v[50:53]
	ds_read_b128 v[82:85], v226 offset:39232
	ds_read_b128 v[70:73], v49 offset:34816
	ds_read_b128 v[74:77], v49 offset:39168
	v_mfma_f32_16x16x32_bf16 v[54:57], v[54:57], v[44:47], 0
	ds_read_b128 v[78:81], v49 offset:43520
	v_cndmask_b32_e64 v87, v105, v230, s[26:27]
	v_cndmask_b32_e64 v88, v105, v230, s[28:29]
	s_waitcnt lgkmcnt(3)
	v_mfma_f32_16x16x32_bf16 v[54:57], v[82:85], v[40:43], v[54:57]
	ds_read_b128 v[82:85], v226 offset:43584
	v_mul_f32_e32 v86, v86, v134
	v_mul_f32_e32 v87, v87, v135
	v_mfma_f32_16x16x32_bf16 v[58:61], v[58:61], v[44:47], 0
	v_mul_f32_e32 v88, v88, v136
	v_exp_f32_e32 v86, v86
	v_exp_f32_e32 v87, v87
	s_waitcnt lgkmcnt(0)
	v_mfma_f32_16x16x32_bf16 v[58:61], v[82:85], v[40:43], v[58:61]
	ds_read_b128 v[82:85], v226 offset:47936
	v_exp_f32_e32 v88, v88
	v_readlane_b32 s68, v255, 4
	v_mfma_f32_16x16x32_bf16 v[62:65], v[62:65], v[44:47], 0
	v_readlane_b32 s69, v255, 5
	s_waitcnt lgkmcnt(0)
	v_mfma_f32_16x16x32_bf16 v[62:65], v[82:85], v[40:43], v[62:65]
	ds_read_b128 v[82:85], v226 offset:52288
	v_cndmask_b32_e64 v239, v105, v230, s[68:69]
	v_readlane_b32 s68, v255, 50
	v_mfma_f32_16x16x32_bf16 v[66:69], v[66:69], v[44:47], 0
	v_readlane_b32 s69, v255, 51
	v_mul_f32_e32 v239, v239, v155
	v_exp_f32_e32 v239, v239
	s_waitcnt lgkmcnt(0)
	v_mfma_f32_16x16x32_bf16 v[66:69], v[82:85], v[40:43], v[66:69]
	ds_read_b128 v[82:85], v49 offset:34880
	v_cndmask_b32_e64 v240, v105, v230, s[68:69]
	v_readlane_b32 s68, v255, 52
	v_mfma_f32_16x16x32_bf16 v[70:73], v[70:73], v[44:47], 0
	v_readlane_b32 s69, v255, 53
	v_mul_f32_e32 v240, v240, v156
	v_exp_f32_e32 v240, v240
	s_waitcnt lgkmcnt(0)
	v_mfma_f32_16x16x32_bf16 v[70:73], v[82:85], v[40:43], v[70:73]
	ds_read_b128 v[82:85], v49 offset:39232
	v_cndmask_b32_e64 v241, v105, v230, s[68:69]
	v_readlane_b32 s68, v255, 54
	v_mfma_f32_16x16x32_bf16 v[74:77], v[74:77], v[44:47], 0
	v_readlane_b32 s69, v255, 55
	v_mul_f32_e32 v241, v241, v157
	v_exp_f32_e32 v241, v241
	s_waitcnt lgkmcnt(0)
	v_mfma_f32_16x16x32_bf16 v[74:77], v[82:85], v[40:43], v[74:77]
	ds_read_b128 v[82:85], v49 offset:43584
	v_cndmask_b32_e64 v242, v105, v230, s[68:69]
	v_readlane_b32 s68, v255, 56
	v_mfma_f32_16x16x32_bf16 v[78:81], v[78:81], v[44:47], 0
	v_readlane_b32 s69, v255, 57
	v_mul_f32_e32 v242, v242, v158
	v_exp_f32_e32 v242, v242
	s_waitcnt lgkmcnt(0)
	v_mfma_f32_16x16x32_bf16 v[78:81], v[82:85], v[40:43], v[78:81]
	ds_read_b128 v[82:85], v226 offset:34944
	v_cndmask_b32_e64 v243, v105, v230, s[68:69]
	v_mul_f32_e32 v243, v243, v159
	s_waitcnt lgkmcnt(0)
	v_mfma_f32_16x16x32_bf16 v[50:53], v[82:85], v[28:31], v[50:53]
	ds_read_b128 v[82:85], v226 offset:39296
	v_exp_f32_e32 v243, v243
	s_waitcnt lgkmcnt(0)
	v_mfma_f32_16x16x32_bf16 v[54:57], v[82:85], v[28:31], v[54:57]
	ds_read_b128 v[82:85], v226 offset:43648
	s_waitcnt lgkmcnt(0)
	v_mfma_f32_16x16x32_bf16 v[58:61], v[82:85], v[28:31], v[58:61]
	ds_read_b128 v[82:85], v226 offset:48000
	s_waitcnt lgkmcnt(0)
	v_mfma_f32_16x16x32_bf16 v[62:65], v[82:85], v[28:31], v[62:65]
	ds_read_b128 v[82:85], v226 offset:52352
	s_waitcnt lgkmcnt(0)
	v_mfma_f32_16x16x32_bf16 v[66:69], v[82:85], v[28:31], v[66:69]
	ds_read_b128 v[82:85], v49 offset:34944
	s_waitcnt lgkmcnt(0)
	v_mfma_f32_16x16x32_bf16 v[70:73], v[82:85], v[28:31], v[70:73]
	ds_read_b128 v[82:85], v49 offset:39296
	s_waitcnt lgkmcnt(0)
	v_mfma_f32_16x16x32_bf16 v[74:77], v[82:85], v[28:31], v[74:77]
	ds_read_b128 v[82:85], v49 offset:43648
	s_waitcnt lgkmcnt(0)
	v_mfma_f32_16x16x32_bf16 v[78:81], v[82:85], v[28:31], v[78:81]
	ds_read_b128 v[82:85], v226 offset:35008
	s_waitcnt lgkmcnt(0)
	v_mfma_f32_16x16x32_bf16 v[50:53], v[82:85], v[0:3], v[50:53]
	ds_read_b128 v[82:85], v226 offset:39360
	s_waitcnt lgkmcnt(0)
; #define LAS __attribute__((address_space(3)))
; __device__ __forceinline__ unsigned pk2(float lo, float hi) { return pg8::cvt_pk_bf16(lo, hi); }
; __device__ __forceinline__ float fexp2(float x) { return __builtin_amdgcn_exp2f(x); }
; #define MFMA16(a, b, c) __builtin_amdgcn_mfma_f32_16x16x32_bf16((a), (b), (c), 0, 0, 0)
; __device__ __forceinline__ void ret_unit(LAS unsigned char* lds, int u, const bf16* PROJ, const int* pos, const float* dec_f, const float* dec_b, const bf16* ST,
;                                          const float* gn_w, const float* gn_b, bf16* MIX, int tid, const WsRef& wsr) {
;     ...
; #pragma unroll
;     for (int n = 0; n < 8; ++n) {
; #pragma unroll
;         for (int r = 0; r < 4; ++r) { const int key = n * 16 + 4 * fq + r; const int df = q - key; const float f = df >= 0 ? fexp2(lgf2 * (float)df) : fexp2(lgb2 * (float)(-df)); s[n][r] *= f; } }
; #pragma unroll
;     for (int kk = 0; kk < 4; ++kk) { u32x4 w; w.x = pk2(s[2 * kk][0], s[2 * kk][1]); w.y = pk2(s[2 * kk][2], s[2 * kk][3]); w.z = pk2(s[2 * kk + 1][0], s[2 * kk + 1][1]); w.w = pk2(s[2 * kk + 1][2], s[2 * kk + 1][3]);
;         pf[kk] = __builtin_bit_cast(bf16x8, w); }
;     f32x4 o[8];
; #pragma unroll
;     for (int n = 0; n < 8; ++n) o[n] = (f32x4){0.f, 0.f, 0.f, 0.f};
; #pragma unroll
;     for (int kk = 0; kk < 4; ++kk)
; #pragma unroll
;         for (int n = 0; n < 8; ++n) { const int sw = (2 * n + (fr >> 3)) & 7, jc = kk * 4 + (fq >> 1); const LAS bf16* vr = VT + (n * 16 + fr) * LDT + 4 * (fq & 1);
;             const u32x2 lo = *(const LAS u32x2*)(vr + ((jc ^ sw) << 3)), hi = *(const LAS u32x2*)(vr + (((jc + 2) ^ sw) << 3)); u32x4 w; w.x = lo.x; w.y = lo.y; w.z = hi.x; w.w = hi.y;
;             o[n] = MFMA16(__builtin_bit_cast(bf16x8, w), pf[kk], o[n]); }
	v_mfma_f32_16x16x32_bf16 v[54:57], v[82:85], v[0:3], v[54:57]
	ds_read_b128 v[82:85], v226 offset:43712
	s_nop 6
	v_pk_mul_f32 v[56:57], v[86:87], v[56:57]
	s_waitcnt lgkmcnt(0)
	v_mfma_f32_16x16x32_bf16 v[58:61], v[82:85], v[0:3], v[58:61]
	ds_read_b128 v[82:85], v226 offset:48064
	s_nop 6
	v_pk_mul_f32 v[58:59], v[88:89], v[58:59]
	s_waitcnt lgkmcnt(0)
	v_mfma_f32_16x16x32_bf16 v[62:65], v[82:85], v[0:3], v[62:65]
	ds_read_b128 v[82:85], v226 offset:52416
	v_pk_mul_f32 v[88:89], v[90:91], v[60:61]
	s_nop 5
	v_pk_mul_f32 v[64:65], v[94:95], v[64:65]
	s_waitcnt lgkmcnt(0)
	v_mfma_f32_16x16x32_bf16 v[66:69], v[82:85], v[0:3], v[66:69]
	ds_read_b128 v[82:85], v49 offset:35008
	v_pk_mul_f32 v[92:93], v[92:93], v[62:63]
	v_cvt_pk_bf16_f32 v63, v56, v57
	v_cvt_pk_bf16_f32 v56, v58, v59
	v_cvt_pk_bf16_f32 v59, v64, v65
	v_add_u32_e32 v64, v160, v161
	ds_read_b64 v[64:65], v64
	s_waitcnt lgkmcnt(1)
	v_mfma_f32_16x16x32_bf16 v[70:73], v[82:85], v[0:3], v[70:73]
	ds_read_b128 v[82:85], v49 offset:39360
	v_cvt_pk_bf16_f32 v58, v92, v93
	v_add_u32_e32 v92, v175, v170
	ds_read_b64 v[92:93], v92
	s_waitcnt lgkmcnt(1)
	v_mfma_f32_16x16x32_bf16 v[74:77], v[82:85], v[0:3], v[74:77]
	ds_read_b128 v[82:85], v49 offset:43712
	v_add_u32_e32 v94, v175, v171
	ds_read_b64 v[94:95], v94
	s_waitcnt lgkmcnt(1)
	v_mfma_f32_16x16x32_bf16 v[78:81], v[82:85], v[0:3], v[78:81]
	v_cndmask_b32_e64 v49, v105, v230, s[44:45]
	v_cndmask_b32_e64 v82, v105, v230, s[46:47]
	v_cndmask_b32_e64 v83, v105, v230, s[48:49]
	v_mul_f32_e32 v49, v49, v129
	v_mul_f32_e32 v82, v82, v231
	v_mul_f32_e32 v83, v83, v252
	v_exp_f32_e32 v49, v49
	v_exp_f32_e32 v82, v82
	v_exp_f32_e32 v83, v83
	v_pk_mul_f32 v[66:67], v[130:131], v[66:67]
	v_pk_mul_f32 v[48:49], v[48:49], v[50:51]
	v_cndmask_b32_e64 v84, v105, v230, s[50:51]
	v_pk_mul_f32 v[50:51], v[82:83], v[52:53]
	v_cvt_pk_bf16_f32 v52, v66, v67
	v_add_u32_e32 v66, v160, v162
	ds_read_b64 v[66:67], v66
	v_cndmask_b32_e64 v85, v105, v230, s[52:53]
	v_mul_f32_e32 v84, v84, v253
	v_mul_f32_e32 v85, v85, v254
	v_exp_f32_e32 v84, v84
	v_exp_f32_e32 v85, v85
	v_cvt_pk_bf16_f32 v60, v48, v49
	v_cvt_pk_bf16_f32 v61, v50, v51
	v_pk_mul_f32 v[80:81], v[242:243], v[80:81]
	v_pk_mul_f32 v[54:55], v[84:85], v[54:55]
	v_cvt_pk_bf16_f32 v51, v80, v81
	v_cvt_pk_bf16_f32 v62, v54, v55
	v_cvt_pk_bf16_f32 v57, v88, v89
	v_pk_mul_f32 v[78:79], v[240:241], v[78:79]
	s_waitcnt lgkmcnt(0)
	v_mfma_f32_16x16x32_bf16 v[84:87], v[64:67], v[60:63], 0
	v_add_u32_e32 v64, v163, v164
	v_add_u32_e32 v66, v163, v165
	ds_read_b64 v[64:65], v64
	ds_read_b64 v[66:67], v66
	s_waitcnt lgkmcnt(0)
	v_mfma_f32_16x16x32_bf16 v[80:83], v[64:67], v[60:63], 0
	v_add_u32_e32 v64, v166, v167
	v_add_u32_e32 v66, v166, v168
	ds_read_b64 v[64:65], v64
	ds_read_b64 v[66:67], v66
	s_waitcnt lgkmcnt(0)
	v_mfma_f32_16x16x32_bf16 v[88:91], v[64:67], v[60:63], 0
	v_add_u32_e32 v64, v169, v170
	v_add_u32_e32 v66, v169, v171
	ds_read_b64 v[64:65], v64
	ds_read_b64 v[66:67], v66
	v_pk_mul_f32 v[76:77], v[238:239], v[76:77]
	v_cvt_pk_bf16_f32 v50, v78, v79
	v_cvt_pk_bf16_f32 v49, v76, v77
	s_waitcnt lgkmcnt(0)
	v_mfma_f32_16x16x32_bf16 v[76:79], v[64:67], v[60:63], 0
	v_add_u32_e32 v64, v172, v161
	v_add_u32_e32 v66, v172, v162
	ds_read_b64 v[64:65], v64
	ds_read_b64 v[66:67], v66
	v_pk_mul_f32 v[74:75], v[236:237], v[74:75]
	v_pk_mul_f32 v[72:73], v[234:235], v[72:73]
	v_cvt_pk_bf16_f32 v48, v74, v75
	v_cvt_pk_bf16_f32 v55, v72, v73
	s_waitcnt lgkmcnt(0)
	v_mfma_f32_16x16x32_bf16 v[72:75], v[64:67], v[60:63], 0
	v_add_u32_e32 v64, v173, v164
	v_add_u32_e32 v66, v173, v165
	ds_read_b64 v[64:65], v64
	ds_read_b64 v[66:67], v66
	v_pk_mul_f32 v[70:71], v[232:233], v[70:71]
	v_pk_mul_f32 v[68:69], v[132:133], v[68:69]
	v_cvt_pk_bf16_f32 v54, v70, v71
	v_cvt_pk_bf16_f32 v53, v68, v69
	s_waitcnt lgkmcnt(0)
	v_mfma_f32_16x16x32_bf16 v[68:71], v[64:67], v[60:63], 0
	v_add_u32_e32 v64, v174, v167
	v_add_u32_e32 v66, v174, v168
	ds_read_b64 v[64:65], v64
	ds_read_b64 v[66:67], v66
	s_waitcnt lgkmcnt(0)
	v_mfma_f32_16x16x32_bf16 v[64:67], v[64:67], v[60:63], 0
	v_mfma_f32_16x16x32_bf16 v[60:63], v[92:95], v[60:63], 0
	v_add_u32_e32 v92, v160, v176
	v_add_u32_e32 v94, v160, v177
	ds_read_b64 v[92:93], v92
	ds_read_b64 v[94:95], v94
	s_waitcnt lgkmcnt(0)
	v_mfma_f32_16x16x32_bf16 v[84:87], v[92:95], v[56:59], v[84:87]
	v_add_u32_e32 v92, v163, v178
	v_add_u32_e32 v94, v163, v179
	ds_read_b64 v[92:93], v92
	ds_read_b64 v[94:95], v94
	s_waitcnt lgkmcnt(0)
	v_mfma_f32_16x16x32_bf16 v[80:83], v[92:95], v[56:59], v[80:83]
	v_add_u32_e32 v92, v166, v180
	v_add_u32_e32 v94, v166, v181
	ds_read_b64 v[92:93], v92
	ds_read_b64 v[94:95], v94
	s_waitcnt lgkmcnt(0)
	v_mfma_f32_16x16x32_bf16 v[88:91], v[92:95], v[56:59], v[88:91]
	v_add_u32_e32 v92, v169, v182
	v_add_u32_e32 v94, v169, v183
	ds_read_b64 v[92:93], v92
	ds_read_b64 v[94:95], v94
	s_waitcnt lgkmcnt(0)
	v_mfma_f32_16x16x32_bf16 v[92:95], v[92:95], v[56:59], v[76:79]
	s_nop 2
	v_add_u32_e32 v76, v172, v176
	v_add_u32_e32 v78, v172, v177
	ds_read_b64 v[76:77], v76
	ds_read_b64 v[78:79], v78
	s_waitcnt lgkmcnt(0)
	v_mfma_f32_16x16x32_bf16 v[72:75], v[76:79], v[56:59], v[72:75]
	v_add_u32_e32 v76, v173, v178
	v_add_u32_e32 v78, v173, v179
	ds_read_b64 v[76:77], v76
	ds_read_b64 v[78:79], v78
	s_waitcnt lgkmcnt(0)
	v_mfma_f32_16x16x32_bf16 v[68:71], v[76:79], v[56:59], v[68:71]
	v_add_u32_e32 v76, v174, v180
	v_add_u32_e32 v78, v174, v181
	ds_read_b64 v[76:77], v76
	ds_read_b64 v[78:79], v78
	s_waitcnt lgkmcnt(0)
	v_mfma_f32_16x16x32_bf16 v[64:67], v[76:79], v[56:59], v[64:67]
	v_add_u32_e32 v76, v175, v182
	v_add_u32_e32 v78, v175, v183
	ds_read_b64 v[76:77], v76
	ds_read_b64 v[78:79], v78
	s_waitcnt lgkmcnt(0)
; #define LAS __attribute__((address_space(3)))
; #define MFMA16(a, b, c) __builtin_amdgcn_mfma_f32_16x16x32_bf16((a), (b), (c), 0, 0, 0)
; __device__ __forceinline__ void ret_unit(LAS unsigned char* lds, int u, const bf16* PROJ, const int* pos, const float* dec_f, const float* dec_b, const bf16* ST,
;                                          const float* gn_w, const float* gn_b, bf16* MIX, int tid, const WsRef& wsr) {
;     ...
;         for (int n = 0; n < 8; ++n) { const int sw = (2 * n + (fr >> 3)) & 7, jc = kk * 4 + (fq >> 1); const LAS bf16* vr = VT + (n * 16 + fr) * LDT + 4 * (fq & 1);
;             const u32x2 lo = *(const LAS u32x2*)(vr + ((jc ^ sw) << 3)), hi = *(const LAS u32x2*)(vr + (((jc + 2) ^ sw) << 3)); u32x4 w; w.x = lo.x; w.y = lo.y; w.z = hi.x; w.w = hi.y;
;             o[n] = MFMA16(__builtin_bit_cast(bf16x8, w), pf[kk], o[n]); }
;     __syncthreads();
; #pragma unroll
;     for (int i = 0; i < 4; ++i) { const int id = tid + 512 * i, e = id >> 4, dch = id & 15;
;         *(LAS u32x4*)(Ks + e * LDT + dch * 8) = sf[i]; *(LAS u32x4*)(VT + e * LDT + dch * 8) = sb[i]; }
;     __syncthreads();
;     {
;         f32x4 tf[8], tb[8];
; #pragma unroll
;         for (int n = 0; n < 8; ++n) { tf[n] = (f32x4){0.f, 0.f, 0.f, 0.f}; tb[n] = (f32x4){0.f, 0.f, 0.f, 0.f}; }
; #pragma unroll
;         for (int kk = 0; kk < 4; ++kk)
; #pragma unroll
;             for (int n = 0; n < 8; ++n) { const bf16x8 yf = *(const LAS bf16x8*)(Ks + (n * 16 + fr) * LDT + kk * 32 + fq * 8); const bf16x8 yb = *(const LAS bf16x8*)(VT + (n * 16 + fr) * LDT + kk * 32 + fq * 8);
;                 tf[n] = MFMA16(yf, qf[kk], tf[n]); tb[n] = MFMA16(yb, qf[kk], tb[n]); }
	v_mfma_f32_16x16x32_bf16 v[56:59], v[76:79], v[56:59], v[60:63]
	v_add_u32_e32 v76, v163, v186
	v_add_u32_e32 v78, v163, v187
	ds_read_b64 v[76:77], v76
	ds_read_b64 v[78:79], v78
	s_waitcnt lgkmcnt(0)
	v_mfma_f32_16x16x32_bf16 v[76:79], v[76:79], v[52:55], v[80:83]
	s_nop 2
	v_add_u32_e32 v80, v166, v188
	v_add_u32_e32 v82, v166, v189
	ds_read_b64 v[80:81], v80
	ds_read_b64 v[82:83], v82
	s_waitcnt lgkmcnt(0)
	v_mfma_f32_16x16x32_bf16 v[80:83], v[80:83], v[52:55], v[88:91]
	s_nop 2
	v_add_u32_e32 v88, v172, v184
	v_add_u32_e32 v90, v172, v185
	ds_read_b64 v[88:89], v88
	ds_read_b64 v[90:91], v90
	s_waitcnt lgkmcnt(0)
	v_mfma_f32_16x16x32_bf16 v[72:75], v[88:91], v[52:55], v[72:75]
	v_add_u32_e32 v88, v173, v186
	v_add_u32_e32 v90, v173, v187
	v_add_u32_e32 v60, v160, v184
	v_add_u32_e32 v62, v160, v185
	ds_read_b64 v[88:89], v88
	ds_read_b64 v[90:91], v90
	ds_read_b64 v[60:61], v60
	ds_read_b64 v[62:63], v62
	s_waitcnt lgkmcnt(2)
	v_mfma_f32_16x16x32_bf16 v[88:91], v[88:91], v[52:55], v[68:71]
	s_nop 2
	v_add_u32_e32 v68, v174, v188
	v_add_u32_e32 v70, v174, v189
	ds_read_b64 v[68:69], v68
	ds_read_b64 v[70:71], v70
	s_waitcnt lgkmcnt(2)
	v_mfma_f32_16x16x32_bf16 v[60:63], v[60:63], v[52:55], v[84:87]
	s_nop 2
	v_add_u32_e32 v84, v169, v190
	v_add_u32_e32 v86, v169, v191
	ds_read_b64 v[84:85], v84
	ds_read_b64 v[86:87], v86
	s_waitcnt lgkmcnt(0)
	v_mfma_f32_16x16x32_bf16 v[84:87], v[84:87], v[52:55], v[92:95]
	v_mfma_f32_16x16x32_bf16 v[92:95], v[68:71], v[52:55], v[64:67]
	v_add_u32_e32 v68, v172, v192
	v_add_u32_e32 v70, v172, v193
	ds_read_b64 v[68:69], v68
	ds_read_b64 v[70:71], v70
	v_add_u32_e32 v64, v175, v190
	v_add_u32_e32 v66, v175, v191
	ds_read_b64 v[64:65], v64
	ds_read_b64 v[66:67], v66
	s_waitcnt lgkmcnt(0)
	v_mfma_f32_16x16x32_bf16 v[232:235], v[64:67], v[52:55], v[56:59]
	v_add_u32_e32 v52, v160, v192
	v_add_u32_e32 v54, v160, v193
	ds_read_b64 v[52:53], v52
	ds_read_b64 v[54:55], v54
	v_add_u32_e32 v56, v163, v194
	v_add_u32_e32 v58, v163, v195
	ds_read_b64 v[56:57], v56
	ds_read_b64 v[58:59], v58
	s_waitcnt lgkmcnt(2)
	v_mfma_f32_16x16x32_bf16 v[52:55], v[52:55], v[48:51], v[60:63]
	s_nop 2
	v_add_u32_e32 v60, v166, v196
	v_add_u32_e32 v62, v166, v197
	ds_read_b64 v[60:61], v60
	ds_read_b64 v[62:63], v62
	v_add_u32_e32 v64, v169, v198
	v_add_u32_e32 v66, v169, v199
	s_waitcnt lgkmcnt(2)
	v_mfma_f32_16x16x32_bf16 v[56:59], v[56:59], v[48:51], v[76:79]
	ds_read_b64 v[64:65], v64
	ds_read_b64 v[66:67], v66
	s_waitcnt lgkmcnt(2)
	v_mfma_f32_16x16x32_bf16 v[60:63], v[60:63], v[48:51], v[80:83]
	v_add_u32_e32 v76, v174, v196
	v_add_u32_e32 v78, v174, v197
	s_nop 0
	v_add_u32_e32 v80, v175, v198
	v_mfma_f32_16x16x32_bf16 v[68:71], v[68:71], v[48:51], v[72:75]
	v_add_u32_e32 v82, v175, v199
	ds_read_b64 v[76:77], v76
	ds_read_b64 v[78:79], v78
	v_add_u32_e32 v72, v173, v194
	v_add_u32_e32 v74, v173, v195
	ds_read_b64 v[72:73], v72
	ds_read_b64 v[74:75], v74
	ds_read_b64 v[80:81], v80
	ds_read_b64 v[82:83], v82
	s_waitcnt lgkmcnt(0)
	s_barrier
	ds_write_b128 v200, v[4:7] offset:34816
	ds_write_b128 v201, v[12:15]
	ds_write_b128 v202, v[8:11] offset:34816
	ds_write_b128 v203, v[16:19]
	ds_write_b128 v205, v[24:27] offset:34816
	ds_write_b128 v206, v[20:23]
	ds_write_b128 v207, v[32:35] offset:34816
	ds_write_b128 v208, v[36:39]
	s_waitcnt lgkmcnt(0)
	s_barrier
	ds_read_b128 v[4:7], v209 offset:34816
	ds_read_b128 v[8:11], v210
	s_waitcnt lgkmcnt(1)
	v_mfma_f32_16x16x32_bf16 v[12:15], v[4:7], v[44:47], 0
	s_waitcnt lgkmcnt(0)
	v_mfma_f32_16x16x32_bf16 v[16:19], v[8:11], v[44:47], 0
	ds_read_b128 v[4:7], v209 offset:39168
	ds_read_b128 v[8:11], v211
	s_waitcnt lgkmcnt(1)
	v_mfma_f32_16x16x32_bf16 v[32:35], v[4:7], v[44:47], 0
	s_waitcnt lgkmcnt(0)
	v_mfma_f32_16x16x32_bf16 v[36:39], v[8:11], v[44:47], 0
	ds_read_b128 v[4:7], v209 offset:43520
	ds_read_b128 v[8:11], v212
	v_mfma_f32_16x16x32_bf16 v[72:75], v[72:75], v[48:51], v[88:91]
	v_mfma_f32_16x16x32_bf16 v[76:79], v[76:79], v[48:51], v[92:95]
	s_waitcnt lgkmcnt(1)
	v_mfma_f32_16x16x32_bf16 v[88:91], v[4:7], v[44:47], 0
	s_waitcnt lgkmcnt(0)
	v_mfma_f32_16x16x32_bf16 v[92:95], v[8:11], v[44:47], 0
	ds_read_b128 v[4:7], v209 offset:47872
	ds_read_b128 v[8:11], v213
	v_mfma_f32_16x16x32_bf16 v[64:67], v[64:67], v[48:51], v[84:87]
	v_mfma_f32_16x16x32_bf16 v[48:51], v[80:83], v[48:51], v[232:235]
	s_waitcnt lgkmcnt(1)
	v_mfma_f32_16x16x32_bf16 v[232:235], v[4:7], v[44:47], 0
	s_waitcnt lgkmcnt(0)
	v_mfma_f32_16x16x32_bf16 v[236:239], v[8:11], v[44:47], 0
	ds_read_b128 v[4:7], v209 offset:52224
	ds_read_b128 v[8:11], v214
	s_waitcnt lgkmcnt(1)
	v_mfma_f32_16x16x32_bf16 v[240:243], v[4:7], v[44:47], 0
	s_waitcnt lgkmcnt(0)
	v_mfma_f32_16x16x32_bf16 v[244:247], v[8:11], v[44:47], 0
	ds_read_b128 v[4:7], v209 offset:56576
	ds_read_b128 v[8:11], v215
	s_waitcnt lgkmcnt(1)
	v_mfma_f32_16x16x32_bf16 v[80:83], v[4:7], v[44:47], 0
	s_waitcnt lgkmcnt(0)
	v_mfma_f32_16x16x32_bf16 v[84:87], v[8:11], v[44:47], 0
	ds_read_b128 v[4:7], v209 offset:60928
	ds_read_b128 v[8:11], v216
	s_waitcnt lgkmcnt(1)
	v_mfma_f32_16x16x32_bf16 v[20:23], v[4:7], v[44:47], 0
	ds_read_b128 v[4:7], v209 offset:65280
	ds_read_b128 v[248:251], v217
	s_waitcnt lgkmcnt(2)
	v_mfma_f32_16x16x32_bf16 v[24:27], v[8:11], v[44:47], 0
	s_waitcnt lgkmcnt(1)
	v_mfma_f32_16x16x32_bf16 v[8:11], v[4:7], v[44:47], 0
	s_waitcnt lgkmcnt(0)
	v_mfma_f32_16x16x32_bf16 v[4:7], v[248:251], v[44:47], 0
	ds_read_b128 v[44:47], v209 offset:34880
	ds_read_b128 v[248:251], v210 offset:64
	s_waitcnt lgkmcnt(1)
	v_mfma_f32_16x16x32_bf16 v[12:15], v[44:47], v[40:43], v[12:15]
	s_waitcnt lgkmcnt(0)
; #define LAS __attribute__((address_space(3)))
; #define MFMA16(a, b, c) __builtin_amdgcn_mfma_f32_16x16x32_bf16((a), (b), (c), 0, 0, 0)
; __device__ __forceinline__ void ret_unit(LAS unsigned char* lds, int u, const bf16* PROJ, const int* pos, const float* dec_f, const float* dec_b, const bf16* ST,
;                                          const float* gn_w, const float* gn_b, bf16* MIX, int tid, const WsRef& wsr) {
;     ...
; #pragma unroll
;         for (int kk = 0; kk < 4; ++kk)
; #pragma unroll
;             for (int n = 0; n < 8; ++n) { const bf16x8 yf = *(const LAS bf16x8*)(Ks + (n * 16 + fr) * LDT + kk * 32 + fq * 8); const bf16x8 yb = *(const LAS bf16x8*)(VT + (n * 16 + fr) * LDT + kk * 32 + fq * 8);
;                 tf[n] = MFMA16(yf, qf[kk], tf[n]); tb[n] = MFMA16(yb, qf[kk], tb[n]); }
	v_mfma_f32_16x16x32_bf16 v[16:19], v[248:251], v[40:43], v[16:19]
	ds_read_b128 v[44:47], v209 offset:39232
	ds_read_b128 v[248:251], v211 offset:64
	s_waitcnt lgkmcnt(1)
	v_mfma_f32_16x16x32_bf16 v[32:35], v[44:47], v[40:43], v[32:35]
	s_waitcnt lgkmcnt(0)
	v_mfma_f32_16x16x32_bf16 v[36:39], v[248:251], v[40:43], v[36:39]
	ds_read_b128 v[44:47], v209 offset:43584
	ds_read_b128 v[248:251], v212 offset:64
	s_waitcnt lgkmcnt(1)
	v_mfma_f32_16x16x32_bf16 v[44:47], v[44:47], v[40:43], v[88:91]
	s_waitcnt lgkmcnt(0)
	v_mfma_f32_16x16x32_bf16 v[88:91], v[248:251], v[40:43], v[92:95]
	s_nop 2
	ds_read_b128 v[92:95], v209 offset:47936
	ds_read_b128 v[248:251], v213 offset:64
	s_waitcnt lgkmcnt(1)
	v_mfma_f32_16x16x32_bf16 v[92:95], v[92:95], v[40:43], v[232:235]
	s_waitcnt lgkmcnt(0)
	v_mfma_f32_16x16x32_bf16 v[232:235], v[248:251], v[40:43], v[236:239]
	s_nop 2
	ds_read_b128 v[236:239], v209 offset:52288
	ds_read_b128 v[248:251], v214 offset:64
	s_waitcnt lgkmcnt(1)
	v_mfma_f32_16x16x32_bf16 v[236:239], v[236:239], v[40:43], v[240:243]
	s_waitcnt lgkmcnt(0)
	v_mfma_f32_16x16x32_bf16 v[240:243], v[248:251], v[40:43], v[244:247]
	s_nop 2
	ds_read_b128 v[244:247], v209 offset:56640
	ds_read_b128 v[248:251], v215 offset:64
	s_waitcnt lgkmcnt(1)
	v_mfma_f32_16x16x32_bf16 v[80:83], v[244:247], v[40:43], v[80:83]
	s_waitcnt lgkmcnt(0)
	v_mfma_f32_16x16x32_bf16 v[84:87], v[248:251], v[40:43], v[84:87]
	ds_read_b128 v[244:247], v209 offset:60992
	ds_read_b128 v[248:251], v216 offset:64
	s_waitcnt lgkmcnt(1)
	v_mfma_f32_16x16x32_bf16 v[244:247], v[244:247], v[40:43], v[20:23]
	s_waitcnt lgkmcnt(0)
	v_mfma_f32_16x16x32_bf16 v[248:251], v[248:251], v[40:43], v[24:27]
	s_nop 0
	ds_read_b128 v[20:23], v209 offset:65344
	s_nop 0
	ds_read_b128 v[24:27], v217 offset:64
	s_waitcnt lgkmcnt(1)
	v_mfma_f32_16x16x32_bf16 v[8:11], v[20:23], v[40:43], v[8:11]
	s_waitcnt lgkmcnt(0)
	v_mfma_f32_16x16x32_bf16 v[4:7], v[24:27], v[40:43], v[4:7]
	ds_read_b128 v[20:23], v209 offset:34944
	ds_read_b128 v[24:27], v210 offset:128
	s_waitcnt lgkmcnt(1)
	v_mfma_f32_16x16x32_bf16 v[40:43], v[20:23], v[28:31], v[12:15]
	s_waitcnt lgkmcnt(0)
	v_mfma_f32_16x16x32_bf16 v[130:133], v[24:27], v[28:31], v[16:19]
	s_nop 0
	ds_read_b128 v[12:15], v209 offset:39296
	s_nop 0
	ds_read_b128 v[16:19], v211 offset:128
	s_waitcnt lgkmcnt(1)
	v_mfma_f32_16x16x32_bf16 v[32:35], v[12:15], v[28:31], v[32:35]
	s_waitcnt lgkmcnt(0)
	v_mfma_f32_16x16x32_bf16 v[36:39], v[16:19], v[28:31], v[36:39]
	ds_read_b128 v[12:15], v209 offset:43648
	ds_read_b128 v[16:19], v212 offset:128
	s_waitcnt lgkmcnt(1)
	v_mfma_f32_16x16x32_bf16 v[44:47], v[12:15], v[28:31], v[44:47]
	s_waitcnt lgkmcnt(0)
	v_mfma_f32_16x16x32_bf16 v[88:91], v[16:19], v[28:31], v[88:91]
	ds_read_b128 v[12:15], v209 offset:48000
	ds_read_b128 v[16:19], v213 offset:128
	s_waitcnt lgkmcnt(1)
	v_mfma_f32_16x16x32_bf16 v[92:95], v[12:15], v[28:31], v[92:95]
	s_waitcnt lgkmcnt(0)
	v_mfma_f32_16x16x32_bf16 v[232:235], v[16:19], v[28:31], v[232:235]
	ds_read_b128 v[12:15], v209 offset:52352
	ds_read_b128 v[16:19], v214 offset:128
	s_waitcnt lgkmcnt(1)
	v_mfma_f32_16x16x32_bf16 v[236:239], v[12:15], v[28:31], v[236:239]
	s_waitcnt lgkmcnt(0)
	v_mfma_f32_16x16x32_bf16 v[240:243], v[16:19], v[28:31], v[240:243]
	ds_read_b128 v[12:15], v209 offset:56704
	ds_read_b128 v[16:19], v215 offset:128
	s_waitcnt lgkmcnt(1)
	v_mfma_f32_16x16x32_bf16 v[20:23], v[12:15], v[28:31], v[80:83]
	s_waitcnt lgkmcnt(0)
	v_mfma_f32_16x16x32_bf16 v[24:27], v[16:19], v[28:31], v[84:87]
	ds_read_b128 v[12:15], v209 offset:61056
	ds_read_b128 v[16:19], v216 offset:128
	ds_read_b128 v[80:83], v209 offset:65408
	ds_read_b128 v[84:87], v217 offset:128
	s_waitcnt lgkmcnt(3)
	v_mfma_f32_16x16x32_bf16 v[12:15], v[12:15], v[28:31], v[244:247]
	s_waitcnt lgkmcnt(2)
	v_mfma_f32_16x16x32_bf16 v[16:19], v[16:19], v[28:31], v[248:251]
	s_waitcnt lgkmcnt(1)
	v_mfma_f32_16x16x32_bf16 v[8:11], v[80:83], v[28:31], v[8:11]
	s_waitcnt lgkmcnt(0)
	v_mfma_f32_16x16x32_bf16 v[4:7], v[84:87], v[28:31], v[4:7]
	ds_read_b128 v[28:31], v209 offset:35008
	ds_read_b128 v[80:83], v210 offset:192
	s_waitcnt lgkmcnt(1)
	v_mfma_f32_16x16x32_bf16 v[28:31], v[28:31], v[0:3], v[40:43]
	s_waitcnt lgkmcnt(0)
	v_mfma_f32_16x16x32_bf16 v[40:43], v[80:83], v[0:3], v[130:133]
	ds_read_b128 v[80:83], v209 offset:39360
	ds_read_b128 v[84:87], v211 offset:192
	s_waitcnt lgkmcnt(1)
	v_mfma_f32_16x16x32_bf16 v[80:83], v[80:83], v[0:3], v[32:35]
	s_waitcnt lgkmcnt(0)
	v_mfma_f32_16x16x32_bf16 v[34:37], v[84:87], v[0:3], v[36:39]
	ds_read_b128 v[84:87], v209 offset:43712
	ds_read_b128 v[130:133], v212 offset:192
	s_waitcnt lgkmcnt(1)
	v_mfma_f32_16x16x32_bf16 v[44:47], v[84:87], v[0:3], v[44:47]
	s_waitcnt lgkmcnt(0)
	v_mfma_f32_16x16x32_bf16 v[84:87], v[130:133], v[0:3], v[88:91]
	s_nop 2
	ds_read_b128 v[88:91], v209 offset:48064
	ds_read_b128 v[130:133], v213 offset:192
	s_waitcnt lgkmcnt(1)
	v_mfma_f32_16x16x32_bf16 v[88:91], v[88:91], v[0:3], v[92:95]
	s_waitcnt lgkmcnt(0)
	v_mfma_f32_16x16x32_bf16 v[92:95], v[130:133], v[0:3], v[232:235]
	ds_read_b128 v[130:133], v209 offset:52416
	s_nop 1
	ds_read_b128 v[232:235], v214 offset:192
	s_waitcnt lgkmcnt(1)
	v_mfma_f32_16x16x32_bf16 v[130:133], v[130:133], v[0:3], v[236:239]
	s_waitcnt lgkmcnt(0)
	v_mfma_f32_16x16x32_bf16 v[232:235], v[232:235], v[0:3], v[240:243]
	s_nop 0
	ds_read_b128 v[236:239], v209 offset:56768
	s_nop 0
	ds_read_b128 v[240:243], v215 offset:192
	s_waitcnt lgkmcnt(1)
	v_mfma_f32_16x16x32_bf16 v[236:239], v[236:239], v[0:3], v[20:23]
	s_waitcnt lgkmcnt(0)
	v_mfma_f32_16x16x32_bf16 v[240:243], v[240:243], v[0:3], v[24:27]
	s_nop 0
	ds_read_b128 v[20:23], v209 offset:61120
	s_nop 0
	ds_read_b128 v[24:27], v216 offset:192
	s_waitcnt lgkmcnt(1)
; __device__ __forceinline__ float fexp2(float x) { return __builtin_amdgcn_exp2f(x); }
; #define MFMA16(a, b, c) __builtin_amdgcn_mfma_f32_16x16x32_bf16((a), (b), (c), 0, 0, 0)
; __device__ __forceinline__ void ret_unit(LAS unsigned char* lds, int u, const bf16* PROJ, const int* pos, const float* dec_f, const float* dec_b, const bf16* ST,
;                                          const float* gn_w, const float* gn_b, bf16* MIX, int tid, const WsRef& wsr) {
;     ...
;                 tf[n] = MFMA16(yf, qf[kk], tf[n]); tb[n] = MFMA16(yb, qf[kk], tb[n]); }
;         const float xif = fexp2(lgf2 * (float)(q + 1)), xib = fexp2(lgb2 * (float)(128 - q));
; #pragma unroll
;         for (int n = 0; n < 8; ++n) o[n] = o[n] + tf[n] * xif + tb[n] * xib;
;     }
;     float sm = 0.f;
; #pragma unroll
;     for (int n = 0; n < 8; ++n) sm += (o[n][0] + o[n][1]) + (o[n][2] + o[n][3]);
;     sm += __shfl_xor(sm, 16); sm += __shfl_xor(sm, 32);
	v_mfma_f32_16x16x32_bf16 v[12:15], v[20:23], v[0:3], v[12:15]
	s_waitcnt lgkmcnt(0)
	v_mfma_f32_16x16x32_bf16 v[244:247], v[24:27], v[0:3], v[16:19]
	s_nop 2
	ds_read_b128 v[16:19], v209 offset:65472
	ds_read_b128 v[20:23], v217 offset:192
	s_waitcnt lgkmcnt(1)
	v_mfma_f32_16x16x32_bf16 v[8:11], v[16:19], v[0:3], v[8:11]
	s_waitcnt lgkmcnt(0)
	v_mfma_f32_16x16x32_bf16 v[248:251], v[20:23], v[0:3], v[4:7]
	v_mul_f32_e32 v0, v105, v218
	v_exp_f32_e32 v38, v0
	v_mul_f32_e32 v0, v230, v219
	v_exp_f32_e32 v230, v0
	v_pk_fma_f32 v[2:3], v[38:39], v[28:29], v[52:53] op_sel_hi:[0,1,1]
	v_pk_fma_f32 v[16:17], v[38:39], v[132:133], v[70:71] op_sel_hi:[0,1,1]
	v_pk_fma_f32 v[0:1], v[38:39], v[30:31], v[54:55] op_sel_hi:[0,1,1]
	v_pk_fma_f32 v[32:33], v[230:231], v[40:41], v[2:3] op_sel_hi:[0,1,1]
	v_pk_fma_f32 v[2:3], v[38:39], v[80:81], v[56:57] op_sel_hi:[0,1,1]
	v_pk_fma_f32 v[18:19], v[38:39], v[130:131], v[68:69] op_sel_hi:[0,1,1]
	v_pk_fma_f32 v[22:23], v[230:231], v[234:235], v[16:17] op_sel_hi:[0,1,1]
	v_pk_fma_f32 v[16:17], v[38:39], v[238:239], v[74:75] op_sel_hi:[0,1,1]
	v_pk_fma_f32 v[12:13], v[38:39], v[12:13], v[76:77] op_sel_hi:[0,1,1]
	v_pk_fma_f32 v[30:31], v[230:231], v[42:43], v[0:1] op_sel_hi:[0,1,1]
	v_pk_fma_f32 v[0:1], v[38:39], v[82:83], v[58:59] op_sel_hi:[0,1,1]
	v_pk_fma_f32 v[28:29], v[230:231], v[34:35], v[2:3] op_sel_hi:[0,1,1]
	v_pk_fma_f32 v[24:25], v[230:231], v[232:233], v[18:19] op_sel_hi:[0,1,1]
	v_pk_fma_f32 v[18:19], v[230:231], v[242:243], v[16:17] op_sel_hi:[0,1,1]
	v_pk_fma_f32 v[16:17], v[230:231], v[244:245], v[12:13] op_sel_hi:[0,1,1]
	v_pk_fma_f32 v[10:11], v[38:39], v[10:11], v[50:51] op_sel_hi:[0,1,1]
	v_pk_fma_f32 v[12:13], v[38:39], v[8:9], v[48:49] op_sel_hi:[0,1,1]
	v_pk_fma_f32 v[26:27], v[230:231], v[36:37], v[0:1] op_sel_hi:[0,1,1]
	v_pk_fma_f32 v[8:9], v[230:231], v[250:251], v[10:11] op_sel_hi:[0,1,1]
	v_pk_fma_f32 v[10:11], v[230:231], v[248:249], v[12:13] op_sel_hi:[0,1,1]
	v_mov_b32_e32 v12, v32
	v_mov_b32_e32 v13, v28
	v_mov_b32_e32 v34, v33
	v_mov_b32_e32 v35, v29
	v_pk_fma_f32 v[0:1], v[38:39], v[46:47], v[62:63] op_sel_hi:[0,1,1]
	v_pk_fma_f32 v[2:3], v[38:39], v[44:45], v[60:61] op_sel_hi:[0,1,1]
	v_pk_add_f32 v[12:13], v[12:13], v[34:35]
	v_mov_b32_e32 v34, v30
	v_mov_b32_e32 v35, v26
	v_mov_b32_e32 v36, v31
	v_mov_b32_e32 v37, v27
	v_pk_fma_f32 v[4:5], v[230:231], v[86:87], v[0:1] op_sel_hi:[0,1,1]
	v_pk_fma_f32 v[6:7], v[230:231], v[84:85], v[2:3] op_sel_hi:[0,1,1]
	v_pk_add_f32 v[34:35], v[34:35], v[36:37]
	v_mov_b32_e32 v36, v6
	v_pk_add_f32 v[12:13], v[12:13], v[34:35]
	v_pk_mov_b32 v[34:35], v[6:7], v[4:5] op_sel:[1,0]
	v_mov_b32_e32 v37, v5
	v_pk_fma_f32 v[0:1], v[38:39], v[90:91], v[66:67] op_sel_hi:[0,1,1]
	v_pk_fma_f32 v[2:3], v[38:39], v[88:89], v[64:65] op_sel_hi:[0,1,1]
	v_pk_add_f32 v[34:35], v[34:35], v[36:37]
	v_pk_fma_f32 v[0:1], v[230:231], v[94:95], v[0:1] op_sel_hi:[0,1,1]
	v_pk_fma_f32 v[2:3], v[230:231], v[92:93], v[2:3] op_sel_hi:[0,1,1]
	v_add_f32_e32 v12, 0, v12
	v_pk_add_f32 v[34:35], v[34:35], v[34:35] op_sel:[0,1] op_sel_hi:[1,0]
	v_pk_fma_f32 v[20:21], v[38:39], v[236:237], v[72:73] op_sel_hi:[0,1,1]
	v_pk_fma_f32 v[14:15], v[38:39], v[14:15], v[78:79] op_sel_hi:[0,1,1]
	v_add_f32_e32 v12, v12, v13
	v_add_f32_e32 v36, v2, v3
	v_add_f32_e32 v38, v0, v1
	v_mov_b32_e32 v13, v24
	v_mov_b32_e32 v35, v25
	v_mov_b32_e32 v37, v22
	v_mov_b32_e32 v39, v23
	v_pk_fma_f32 v[20:21], v[230:231], v[240:241], v[20:21] op_sel_hi:[0,1,1]
	v_pk_add_f32 v[12:13], v[12:13], v[34:35]
	v_pk_add_f32 v[34:35], v[36:37], v[38:39]
	v_mov_b32_e32 v36, v20
	v_pk_add_f32 v[12:13], v[12:13], v[34:35]
	v_pk_mov_b32 v[34:35], v[20:21], v[18:19] op_sel:[1,0]
	v_mov_b32_e32 v37, v19
	v_pk_add_f32 v[34:35], v[34:35], v[36:37]
	v_pk_fma_f32 v[14:15], v[230:231], v[246:247], v[14:15] op_sel_hi:[0,1,1]
	v_pk_add_f32 v[12:13], v[12:13], v[12:13] op_sel:[0,1] op_sel_hi:[1,0]
	v_pk_add_f32 v[34:35], v[34:35], v[34:35] op_sel:[0,1] op_sel_hi:[1,0]
	v_add_f32_e32 v36, v16, v17
	v_add_f32_e32 v38, v14, v15
	v_mov_b32_e32 v13, v10
	v_mov_b32_e32 v35, v11
	v_mov_b32_e32 v37, v8
	v_mov_b32_e32 v39, v9
	v_pk_add_f32 v[12:13], v[12:13], v[34:35]
	v_pk_add_f32 v[34:35], v[36:37], v[38:39]
	v_or_b32_e32 v48, s0, v126
	v_pk_add_f32 v[12:13], v[12:13], v[34:35]
	v_mov_b32_e32 v49, v97
	v_add_f32_e32 v12, v12, v13
	ds_bpermute_b32 v13, v220, v12
	s_waitcnt lgkmcnt(0)
	v_add_f32_e32 v12, v12, v13
	ds_bpermute_b32 v13, v221, v12
	s_waitcnt lgkmcnt(0)
; __device__ __forceinline__ unsigned pk2(float lo, float hi) { return pg8::cvt_pk_bf16(lo, hi); }
; __device__ __forceinline__ float bflo(unsigned w) { return __uint_as_float(w << 16); }
; __device__ __forceinline__ float bfhi(unsigned w) { return __uint_as_float(w & 0xffff0000u); }
; __device__ __forceinline__ void ret_unit(LAS unsigned char* lds, int u, const bf16* PROJ, const int* pos, const float* dec_f, const float* dec_b, const bf16* ST,
;                                          const float* gn_w, const float* gn_b, bf16* MIX, int tid, const WsRef& wsr) {
;     ...
;     const float mu = sm * (1.f / 128.f);
;     float vq = 0.f;
; #pragma unroll
;     for (int n = 0; n < 8; ++n) { const f32x4 d = o[n] - mu; vq += (d[0] * d[0] + d[1] * d[1]) + (d[2] * d[2] + d[3] * d[3]); }
;     vq += __shfl_xor(vq, 16); vq += __shfl_xor(vq, 32);
;     const float rstd = rsqrtf(vq * (1.f / 128.f) + EPS);
;     const size_t row = row0 + q;
; #pragma unroll
;     for (int n = 0; n < 8; ++n) { const int col = h * 128 + n * 16 + 4 * fq;
;         const f32x4 gw = *(const f32x4*)(gn_w + col), gb = *(const f32x4*)(gn_b + col);
;         const u32x2 gg = *(const u32x2*)(PROJ + row * INC + 1536 + col);
;         const f32x4 g = (f32x4){bflo(gg.x), bfhi(gg.x), bflo(gg.y), bfhi(gg.y)};
;         f32x4 y = (o[n] - mu) * rstd * gw + gb;
; #pragma unroll
;         for (int r = 0; r < 4; ++r) y[r] = y[r] * g[r] * __builtin_amdgcn_rcpf(1.f + __expf(-g[r]));
;         u32x2 w; w.x = pk2(y[0], y[1]); w.y = pk2(y[2], y[3]); *(u32x2*)(MIX + row * D + col) = w; }
	v_add_f32_e32 v40, v12, v13
	v_fmamk_f32 v33, v40, 0xbc000000, v33
	v_fmamk_f32 v29, v40, 0xbc000000, v29
	v_fmamk_f32 v31, v40, 0xbc000000, v31
	v_fmac_f32_e32 v32, 0xbc000000, v40
	v_fmamk_f32 v27, v40, 0xbc000000, v27
	v_fmac_f32_e32 v28, 0xbc000000, v40
	v_mov_b32_e32 v34, v33
	v_mov_b32_e32 v35, v29
	v_fmac_f32_e32 v30, 0xbc000000, v40
	v_fmac_f32_e32 v26, 0xbc000000, v40
	v_mov_b32_e32 v12, v32
	v_mov_b32_e32 v13, v28
	v_pk_mul_f32 v[34:35], v[34:35], v[34:35]
	v_mov_b32_e32 v36, v31
	v_mov_b32_e32 v37, v27
	v_pk_fma_f32 v[12:13], v[12:13], v[12:13], v[34:35]
	v_mov_b32_e32 v34, v30
	v_mov_b32_e32 v35, v26
	v_pk_mul_f32 v[36:37], v[36:37], v[36:37]
	v_fmamk_f32 v7, v40, 0xbc000000, v7
	v_pk_fma_f32 v[34:35], v[34:35], v[34:35], v[36:37]
	v_fmac_f32_e32 v6, 0xbc000000, v40
	v_pk_add_f32 v[12:13], v[12:13], v[34:35]
	v_fmamk_f32 v5, v40, 0xbc000000, v5
	v_fmac_f32_e32 v4, 0xbc000000, v40
	v_pk_add_f32 v[12:13], v[12:13], v[12:13] op_sel_hi:[0,1]
	v_pk_mul_f32 v[34:35], v[4:5], v[4:5]
	v_pk_mul_f32 v[36:37], v[6:7], v[6:7]
	v_fmac_f32_e32 v2, 0xbc000000, v40
	v_pk_mov_b32 v[38:39], v[36:37], v[34:35] op_sel:[1,0]
	v_mov_b32_e32 v37, v35
	v_fmamk_f32 v3, v40, 0xbc000000, v3
	v_fmac_f32_e32 v0, 0xbc000000, v40
	v_mul_f32_e32 v12, v2, v2
	v_pk_add_f32 v[34:35], v[38:39], v[36:37]
	v_fmamk_f32 v1, v40, 0xbc000000, v1
	v_pk_fma_f32 v[36:37], v[2:3], v[2:3], v[12:13] op_sel_hi:[1,1,0]
	v_mul_f32_e32 v12, v0, v0
	v_pk_add_f32 v[34:35], v[34:35], v[34:35] op_sel_hi:[0,1]
	v_pk_fma_f32 v[38:39], v[0:1], v[0:1], v[12:13] op_sel_hi:[1,1,0]
	v_fmamk_f32 v23, v40, 0xbc000000, v23
	v_fmac_f32_e32 v22, 0xbc000000, v40
	v_fmamk_f32 v25, v40, 0xbc000000, v25
	v_fmac_f32_e32 v24, 0xbc000000, v40
	v_mul_f32_e32 v36, v24, v24
	v_mul_f32_e32 v38, v25, v25
	v_mul_f32_e32 v34, v22, v22
	v_mul_f32_e32 v12, v23, v23
	v_pk_add_f32 v[36:37], v[36:37], v[38:39]
	v_pk_add_f32 v[12:13], v[34:35], v[12:13]
	v_fmamk_f32 v21, v40, 0xbc000000, v21
	v_pk_add_f32 v[12:13], v[36:37], v[12:13]
	v_fmac_f32_e32 v20, 0xbc000000, v40
	v_fmamk_f32 v19, v40, 0xbc000000, v19
	v_fmac_f32_e32 v18, 0xbc000000, v40
	v_pk_add_f32 v[12:13], v[12:13], v[12:13] op_sel_hi:[0,1]
	v_pk_mul_f32 v[34:35], v[18:19], v[18:19]
	v_pk_mul_f32 v[36:37], v[20:21], v[20:21]
	v_fmac_f32_e32 v16, 0xbc000000, v40
	v_pk_mov_b32 v[38:39], v[36:37], v[34:35] op_sel:[1,0]
	v_mov_b32_e32 v37, v35
	v_fmamk_f32 v17, v40, 0xbc000000, v17
	v_fmac_f32_e32 v14, 0xbc000000, v40
	v_mul_f32_e32 v12, v16, v16
	v_pk_add_f32 v[34:35], v[38:39], v[36:37]
	v_fmamk_f32 v15, v40, 0xbc000000, v15
	v_pk_fma_f32 v[36:37], v[16:17], v[16:17], v[12:13] op_sel_hi:[1,1,0]
	v_mul_f32_e32 v12, v14, v14
	v_pk_add_f32 v[34:35], v[34:35], v[34:35] op_sel_hi:[0,1]
	v_pk_fma_f32 v[38:39], v[14:15], v[14:15], v[12:13] op_sel_hi:[1,1,0]
	v_fmamk_f32 v9, v40, 0xbc000000, v9
	v_fmac_f32_e32 v8, 0xbc000000, v40
	v_fmamk_f32 v11, v40, 0xbc000000, v11
	v_fmac_f32_e32 v10, 0xbc000000, v40
	v_mul_f32_e32 v36, v10, v10
	v_mul_f32_e32 v38, v11, v11
	v_mul_f32_e32 v34, v8, v8
	v_mul_f32_e32 v12, v9, v9
	v_pk_add_f32 v[36:37], v[36:37], v[38:39]
	v_pk_add_f32 v[12:13], v[34:35], v[12:13]
	v_lshl_add_u64 v[34:35], s[4:5], 0, v[102:103]
	v_pk_add_f32 v[12:13], v[36:37], v[12:13]
	v_mov_b64_e32 v[36:37], s[6:7]
	v_add_f32_e32 v12, v12, v13
	ds_bpermute_b32 v13, v220, v12
	s_waitcnt lgkmcnt(0)
	v_add_f32_e32 v12, v12, v13
	ds_bpermute_b32 v13, v221, v12
	s_waitcnt lgkmcnt(0)
	v_add_f32_e32 v12, v12, v13
	v_fmamk_f32 v12, v12, 0x3c000000, v227
	v_cmp_gt_f32_e64 s[68:69], s1, v12
	v_mul_f32_e32 v13, 0x4b800000, v12
	v_mad_u64_u32 v[44:45], s[0:1], v34, s72, v[36:37]
	v_cndmask_b32_e64 v12, v12, v13, s[68:69]
	v_rsq_f32_e32 v12, v12
	v_mad_i32_i24 v45, v35, s72, v45
	v_lshlrev_b64 v[34:35], 11, v[34:35]
	v_lshl_add_u64 v[46:47], s[70:71], 0, v[34:35]
	v_mul_f32_e32 v13, 0x45800000, v12
	v_cndmask_b32_e64 v12, v12, v13, s[68:69]
	v_lshlrev_b32_e32 v13, 2, v48
	v_lshlrev_b32_e32 v48, 1, v48
	v_lshl_add_u64 v[34:35], v[44:45], 0, v[48:49]
	v_lshl_add_u64 v[46:47], v[46:47], 0, v[48:49]
	v_mbcnt_lo_u32_b32 v130, -1, 0
	v_mbcnt_hi_u32_b32 v130, -1, v130
	v_and_b32_e32 v130, 16, v130
	v_lshrrev_b32_e32 v131, 1, v130
	v_add_u32_e32 v130, v130, v131
	v_mov_b32_e32 v131, 0
	v_lshl_add_u64 v[46:47], v[46:47], 0, v[130:131]
	global_load_dwordx2 v[56:57], v[34:35], off offset:3072
	global_load_dwordx2 v[58:59], v[34:35], off offset:3104
	global_load_dwordx2 v[60:61], v[34:35], off offset:3136
	global_load_dwordx2 v[62:63], v[34:35], off offset:3168
	global_load_dwordx2 v[64:65], v[34:35], off offset:3200
	global_load_dwordx2 v[66:67], v[34:35], off offset:3232
	global_load_dwordx2 v[68:69], v[34:35], off offset:3264
	global_load_dwordx2 v[70:71], v[34:35], off offset:3296
	global_load_dwordx4 v[72:75], v13, s[22:23]
	global_load_dwordx4 v[76:79], v13, s[36:37]
	global_load_dwordx4 v[80:83], v13, s[22:23] offset:64
	global_load_dwordx4 v[84:87], v13, s[36:37] offset:64
	global_load_dwordx4 v[88:91], v13, s[22:23] offset:128
	global_load_dwordx4 v[92:95], v13, s[36:37] offset:128
	global_load_dwordx4 v[36:39], v13, s[22:23] offset:192
	global_load_dwordx4 v[40:43], v13, s[36:37] offset:192
	global_load_dwordx4 v[232:235], v13, s[22:23] offset:256
	global_load_dwordx4 v[236:239], v13, s[36:37] offset:256
	global_load_dwordx4 v[240:243], v13, s[22:23] offset:320
	global_load_dwordx4 v[248:251], v13, s[36:37] offset:320
	v_pk_mul_f32 v[32:33], v[32:33], v[12:13] op_sel_hi:[1,0]
	v_pk_mul_f32 v[30:31], v[30:31], v[12:13] op_sel_hi:[1,0]
	v_pk_mul_f32 v[28:29], v[28:29], v[12:13] op_sel_hi:[1,0]
	v_pk_mul_f32 v[26:27], v[26:27], v[12:13] op_sel_hi:[1,0]
	v_pk_mul_f32 v[6:7], v[6:7], v[12:13] op_sel_hi:[1,0]
	v_pk_mul_f32 v[4:5], v[4:5], v[12:13] op_sel_hi:[1,0]
	v_pk_mul_f32 v[2:3], v[2:3], v[12:13] op_sel_hi:[1,0]
	v_pk_mul_f32 v[0:1], v[0:1], v[12:13] op_sel_hi:[1,0]
	v_pk_mul_f32 v[24:25], v[24:25], v[12:13] op_sel_hi:[1,0]
	v_pk_mul_f32 v[22:23], v[22:23], v[12:13] op_sel_hi:[1,0]
	v_pk_mul_f32 v[20:21], v[20:21], v[12:13] op_sel_hi:[1,0]
	v_pk_mul_f32 v[18:19], v[18:19], v[12:13] op_sel_hi:[1,0]
	v_pk_mul_f32 v[16:17], v[16:17], v[12:13] op_sel_hi:[1,0]
	v_pk_mul_f32 v[14:15], v[14:15], v[12:13] op_sel_hi:[1,0]
	v_pk_mul_f32 v[10:11], v[10:11], v[12:13] op_sel_hi:[1,0]
	v_pk_mul_f32 v[8:9], v[8:9], v[12:13] op_sel_hi:[1,0]
	s_waitcnt vmcnt(10)
; __device__ __forceinline__ unsigned pk2(float lo, float hi) { return pg8::cvt_pk_bf16(lo, hi); }
; __device__ __forceinline__ float bflo(unsigned w) { return __uint_as_float(w << 16); }
; __device__ __forceinline__ float bfhi(unsigned w) { return __uint_as_float(w & 0xffff0000u); }
; __device__ __forceinline__ void ret_unit(LAS unsigned char* lds, int u, const bf16* PROJ, const int* pos, const float* dec_f, const float* dec_b, const bf16* ST,
;                                          const float* gn_w, const float* gn_b, bf16* MIX, int tid, const WsRef& wsr) {
;     ...
;     for (int n = 0; n < 8; ++n) { const int col = h * 128 + n * 16 + 4 * fq;
;         const f32x4 gw = *(const f32x4*)(gn_w + col), gb = *(const f32x4*)(gn_b + col);
;         const u32x2 gg = *(const u32x2*)(PROJ + row * INC + 1536 + col);
;         const f32x4 g = (f32x4){bflo(gg.x), bfhi(gg.x), bflo(gg.y), bfhi(gg.y)};
;         f32x4 y = (o[n] - mu) * rstd * gw + gb;
; #pragma unroll
;         for (int r = 0; r < 4; ++r) y[r] = y[r] * g[r] * __builtin_amdgcn_rcpf(1.f + __expf(-g[r]));
;         u32x2 w; w.x = pk2(y[0], y[1]); w.y = pk2(y[2], y[3]); *(u32x2*)(MIX + row * D + col) = w; }
	v_lshlrev_b32_e32 v130, 16, v56
	v_and_b32_e32 v131, 0xffff0000, v56
	v_lshlrev_b32_e32 v132, 16, v57
	v_and_b32_e32 v133, 0xffff0000, v57
	v_pk_fma_f32 v[32:33], v[72:73], v[32:33], v[76:77]
	v_pk_fma_f32 v[30:31], v[74:75], v[30:31], v[78:79]
	global_load_dwordx4 v[72:75], v13, s[22:23] offset:384
	global_load_dwordx4 v[76:79], v13, s[36:37] offset:384
	v_mul_f32_e32 v56, 0xbfb8aa3b, v130
	v_mul_f32_e32 v57, 0xbfb8aa3b, v131
	v_exp_f32_e32 v56, v56
	v_exp_f32_e32 v57, v57
	v_pk_mul_f32 v[32:33], v[32:33], v[130:131]
	v_mul_f32_e32 v130, 0xbfb8aa3b, v132
	v_mul_f32_e32 v131, 0xbfb8aa3b, v133
	v_add_f32_e32 v56, 1.0, v56
	v_add_f32_e32 v57, 1.0, v57
	v_rcp_f32_e32 v56, v56
	v_rcp_f32_e32 v57, v57
	v_exp_f32_e32 v130, v130
	v_exp_f32_e32 v131, v131
	v_pk_mul_f32 v[30:31], v[30:31], v[132:133]
	v_pk_mul_f32 v[32:33], v[56:57], v[32:33]
	v_add_f32_e32 v130, 1.0, v130
	v_add_f32_e32 v131, 1.0, v131
	v_rcp_f32_e32 v130, v130
	v_rcp_f32_e32 v131, v131
	v_cvt_pk_bf16_f32 v56, v32, v33
	s_nop 0
	v_pk_mul_f32 v[30:31], v[130:131], v[30:31]
	s_nop 0
	v_cvt_pk_bf16_f32 v57, v30, v31
	s_waitcnt vmcnt(10)
	v_lshlrev_b32_e32 v130, 16, v58
	v_and_b32_e32 v131, 0xffff0000, v58
	v_lshlrev_b32_e32 v132, 16, v59
	v_and_b32_e32 v133, 0xffff0000, v59
	v_pk_fma_f32 v[28:29], v[80:81], v[28:29], v[84:85]
	v_pk_fma_f32 v[26:27], v[82:83], v[26:27], v[86:87]
	global_load_dwordx4 v[80:83], v13, s[22:23] offset:448
	global_load_dwordx4 v[84:87], v13, s[36:37] offset:448
	v_mul_f32_e32 v58, 0xbfb8aa3b, v130
	v_mul_f32_e32 v59, 0xbfb8aa3b, v131
	v_exp_f32_e32 v58, v58
	v_exp_f32_e32 v59, v59
	v_pk_mul_f32 v[28:29], v[28:29], v[130:131]
	v_mul_f32_e32 v130, 0xbfb8aa3b, v132
	v_mul_f32_e32 v131, 0xbfb8aa3b, v133
	v_add_f32_e32 v58, 1.0, v58
	v_add_f32_e32 v59, 1.0, v59
	v_rcp_f32_e32 v58, v58
	v_rcp_f32_e32 v59, v59
	v_exp_f32_e32 v130, v130
	v_exp_f32_e32 v131, v131
	v_pk_mul_f32 v[26:27], v[26:27], v[132:133]
	v_pk_mul_f32 v[28:29], v[58:59], v[28:29]
	v_add_f32_e32 v130, 1.0, v130
	v_add_f32_e32 v131, 1.0, v131
	v_rcp_f32_e32 v130, v130
	v_rcp_f32_e32 v131, v131
	v_cvt_pk_bf16_f32 v58, v28, v29
	s_nop 0
	v_pk_mul_f32 v[26:27], v[130:131], v[26:27]
	s_nop 0
	v_cvt_pk_bf16_f32 v59, v26, v27
	s_nop 1
	v_permlane16_swap_b32_e32 v56, v58
	v_permlane16_swap_b32_e32 v57, v59
	global_store_dwordx4 v[46:47], v[56:59], off
	s_waitcnt vmcnt(11)
	v_lshlrev_b32_e32 v130, 16, v60
	v_and_b32_e32 v131, 0xffff0000, v60
	v_lshlrev_b32_e32 v132, 16, v61
	v_and_b32_e32 v133, 0xffff0000, v61
	v_pk_fma_f32 v[6:7], v[88:89], v[6:7], v[92:93]
	v_pk_fma_f32 v[4:5], v[90:91], v[4:5], v[94:95]
	v_mul_f32_e32 v60, 0xbfb8aa3b, v130
	v_mul_f32_e32 v61, 0xbfb8aa3b, v131
	v_exp_f32_e32 v60, v60
	v_exp_f32_e32 v61, v61
	v_pk_mul_f32 v[6:7], v[6:7], v[130:131]
	v_mul_f32_e32 v130, 0xbfb8aa3b, v132
	v_mul_f32_e32 v131, 0xbfb8aa3b, v133
	v_add_f32_e32 v60, 1.0, v60
	v_add_f32_e32 v61, 1.0, v61
	v_rcp_f32_e32 v60, v60
	v_rcp_f32_e32 v61, v61
	v_exp_f32_e32 v130, v130
	v_exp_f32_e32 v131, v131
	v_pk_mul_f32 v[4:5], v[4:5], v[132:133]
	v_pk_mul_f32 v[6:7], v[60:61], v[6:7]
	v_add_f32_e32 v130, 1.0, v130
	v_add_f32_e32 v131, 1.0, v131
	v_rcp_f32_e32 v130, v130
	v_rcp_f32_e32 v131, v131
	v_cvt_pk_bf16_f32 v60, v6, v7
	s_nop 0
	v_pk_mul_f32 v[4:5], v[130:131], v[4:5]
	s_nop 0
	v_cvt_pk_bf16_f32 v61, v4, v5
	s_waitcnt vmcnt(9)
	v_lshlrev_b32_e32 v130, 16, v62
	v_and_b32_e32 v131, 0xffff0000, v62
	v_lshlrev_b32_e32 v132, 16, v63
	v_and_b32_e32 v133, 0xffff0000, v63
	v_pk_fma_f32 v[2:3], v[36:37], v[2:3], v[40:41]
	v_pk_fma_f32 v[0:1], v[38:39], v[0:1], v[42:43]
	v_mul_f32_e32 v62, 0xbfb8aa3b, v130
	v_mul_f32_e32 v63, 0xbfb8aa3b, v131
	v_exp_f32_e32 v62, v62
	v_exp_f32_e32 v63, v63
	v_pk_mul_f32 v[2:3], v[2:3], v[130:131]
	v_mul_f32_e32 v130, 0xbfb8aa3b, v132
	v_mul_f32_e32 v131, 0xbfb8aa3b, v133
	v_add_f32_e32 v62, 1.0, v62
	v_add_f32_e32 v63, 1.0, v63
	v_rcp_f32_e32 v62, v62
	v_rcp_f32_e32 v63, v63
	v_exp_f32_e32 v130, v130
	v_exp_f32_e32 v131, v131
	v_pk_mul_f32 v[0:1], v[0:1], v[132:133]
	v_pk_mul_f32 v[2:3], v[62:63], v[2:3]
	v_add_f32_e32 v130, 1.0, v130
	v_add_f32_e32 v131, 1.0, v131
	v_rcp_f32_e32 v130, v130
	v_rcp_f32_e32 v131, v131
	v_cvt_pk_bf16_f32 v62, v2, v3
	s_nop 0
	v_pk_mul_f32 v[0:1], v[130:131], v[0:1]
	s_nop 0
	v_cvt_pk_bf16_f32 v63, v0, v1
	s_nop 1
	v_permlane16_swap_b32_e32 v60, v62
	v_permlane16_swap_b32_e32 v61, v63
	global_store_dwordx4 v[46:47], v[60:63], off offset:64
	s_waitcnt vmcnt(8)
; __device__ __forceinline__ unsigned pk2(float lo, float hi) { return pg8::cvt_pk_bf16(lo, hi); }
; __device__ __forceinline__ float bflo(unsigned w) { return __uint_as_float(w << 16); }
; __device__ __forceinline__ float bfhi(unsigned w) { return __uint_as_float(w & 0xffff0000u); }
; __device__ __forceinline__ void ret_unit(LAS unsigned char* lds, int u, const bf16* PROJ, const int* pos, const float* dec_f, const float* dec_b, const bf16* ST,
;                                          const float* gn_w, const float* gn_b, bf16* MIX, int tid, const WsRef& wsr) {
;     ...
;     for (int n = 0; n < 8; ++n) { const int col = h * 128 + n * 16 + 4 * fq;
;         const f32x4 gw = *(const f32x4*)(gn_w + col), gb = *(const f32x4*)(gn_b + col);
;         const u32x2 gg = *(const u32x2*)(PROJ + row * INC + 1536 + col);
;         const f32x4 g = (f32x4){bflo(gg.x), bfhi(gg.x), bflo(gg.y), bfhi(gg.y)};
;         f32x4 y = (o[n] - mu) * rstd * gw + gb;
; #pragma unroll
;         for (int r = 0; r < 4; ++r) y[r] = y[r] * g[r] * __builtin_amdgcn_rcpf(1.f + __expf(-g[r]));
;         u32x2 w; w.x = pk2(y[0], y[1]); w.y = pk2(y[2], y[3]); *(u32x2*)(MIX + row * D + col) = w; }
;     __syncthreads();
	v_lshlrev_b32_e32 v130, 16, v64
	v_and_b32_e32 v131, 0xffff0000, v64
	v_lshlrev_b32_e32 v132, 16, v65
	v_and_b32_e32 v133, 0xffff0000, v65
	v_pk_fma_f32 v[24:25], v[232:233], v[24:25], v[236:237]
	v_pk_fma_f32 v[22:23], v[234:235], v[22:23], v[238:239]
	v_mul_f32_e32 v64, 0xbfb8aa3b, v130
	v_mul_f32_e32 v65, 0xbfb8aa3b, v131
	v_exp_f32_e32 v64, v64
	v_exp_f32_e32 v65, v65
	v_pk_mul_f32 v[24:25], v[24:25], v[130:131]
	v_mul_f32_e32 v130, 0xbfb8aa3b, v132
	v_mul_f32_e32 v131, 0xbfb8aa3b, v133
	v_add_f32_e32 v64, 1.0, v64
	v_add_f32_e32 v65, 1.0, v65
	v_rcp_f32_e32 v64, v64
	v_rcp_f32_e32 v65, v65
	v_exp_f32_e32 v130, v130
	v_exp_f32_e32 v131, v131
	v_pk_mul_f32 v[22:23], v[22:23], v[132:133]
	v_pk_mul_f32 v[24:25], v[64:65], v[24:25]
	v_add_f32_e32 v130, 1.0, v130
	v_add_f32_e32 v131, 1.0, v131
	v_rcp_f32_e32 v130, v130
	v_rcp_f32_e32 v131, v131
	v_cvt_pk_bf16_f32 v64, v24, v25
	s_nop 0
	v_pk_mul_f32 v[22:23], v[130:131], v[22:23]
	s_nop 0
	v_cvt_pk_bf16_f32 v65, v22, v23
	s_waitcnt vmcnt(6)
	v_lshlrev_b32_e32 v130, 16, v66
	v_and_b32_e32 v131, 0xffff0000, v66
	v_lshlrev_b32_e32 v132, 16, v67
	v_and_b32_e32 v133, 0xffff0000, v67
	v_pk_fma_f32 v[20:21], v[240:241], v[20:21], v[248:249]
	v_pk_fma_f32 v[18:19], v[242:243], v[18:19], v[250:251]
	v_mul_f32_e32 v66, 0xbfb8aa3b, v130
	v_mul_f32_e32 v67, 0xbfb8aa3b, v131
	v_exp_f32_e32 v66, v66
	v_exp_f32_e32 v67, v67
	v_pk_mul_f32 v[20:21], v[20:21], v[130:131]
	v_mul_f32_e32 v130, 0xbfb8aa3b, v132
	v_mul_f32_e32 v131, 0xbfb8aa3b, v133
	v_add_f32_e32 v66, 1.0, v66
	v_add_f32_e32 v67, 1.0, v67
	v_rcp_f32_e32 v66, v66
	v_rcp_f32_e32 v67, v67
	v_exp_f32_e32 v130, v130
	v_exp_f32_e32 v131, v131
	v_pk_mul_f32 v[18:19], v[18:19], v[132:133]
	v_pk_mul_f32 v[20:21], v[66:67], v[20:21]
	v_add_f32_e32 v130, 1.0, v130
	v_add_f32_e32 v131, 1.0, v131
	v_rcp_f32_e32 v130, v130
	v_rcp_f32_e32 v131, v131
	v_cvt_pk_bf16_f32 v66, v20, v21
	s_nop 0
	v_pk_mul_f32 v[18:19], v[130:131], v[18:19]
	s_nop 0
	v_cvt_pk_bf16_f32 v67, v18, v19
	s_nop 1
	v_permlane16_swap_b32_e32 v64, v66
	v_permlane16_swap_b32_e32 v65, v67
	global_store_dwordx4 v[46:47], v[64:67], off offset:128
	s_waitcnt vmcnt(5)
	v_lshlrev_b32_e32 v130, 16, v68
	v_and_b32_e32 v131, 0xffff0000, v68
	v_lshlrev_b32_e32 v132, 16, v69
	v_and_b32_e32 v133, 0xffff0000, v69
	v_pk_fma_f32 v[16:17], v[72:73], v[16:17], v[76:77]
	v_pk_fma_f32 v[14:15], v[74:75], v[14:15], v[78:79]
	v_mul_f32_e32 v68, 0xbfb8aa3b, v130
	v_mul_f32_e32 v69, 0xbfb8aa3b, v131
	v_exp_f32_e32 v68, v68
	v_exp_f32_e32 v69, v69
	v_pk_mul_f32 v[16:17], v[16:17], v[130:131]
	v_mul_f32_e32 v130, 0xbfb8aa3b, v132
	v_mul_f32_e32 v131, 0xbfb8aa3b, v133
	v_add_f32_e32 v68, 1.0, v68
	v_add_f32_e32 v69, 1.0, v69
	v_rcp_f32_e32 v68, v68
	v_rcp_f32_e32 v69, v69
	v_exp_f32_e32 v130, v130
	v_exp_f32_e32 v131, v131
	v_pk_mul_f32 v[14:15], v[14:15], v[132:133]
	v_pk_mul_f32 v[16:17], v[68:69], v[16:17]
	v_add_f32_e32 v130, 1.0, v130
	v_add_f32_e32 v131, 1.0, v131
	v_rcp_f32_e32 v130, v130
	v_rcp_f32_e32 v131, v131
	v_cvt_pk_bf16_f32 v68, v16, v17
	s_nop 0
	v_pk_mul_f32 v[14:15], v[130:131], v[14:15]
	s_nop 0
	v_cvt_pk_bf16_f32 v69, v14, v15
	s_waitcnt vmcnt(3)
	v_lshlrev_b32_e32 v130, 16, v70
	v_and_b32_e32 v131, 0xffff0000, v70
	v_lshlrev_b32_e32 v132, 16, v71
	v_and_b32_e32 v133, 0xffff0000, v71
	v_pk_fma_f32 v[10:11], v[80:81], v[10:11], v[84:85]
	v_pk_fma_f32 v[8:9], v[82:83], v[8:9], v[86:87]
	v_mul_f32_e32 v70, 0xbfb8aa3b, v130
	v_mul_f32_e32 v71, 0xbfb8aa3b, v131
	v_exp_f32_e32 v70, v70
	v_exp_f32_e32 v71, v71
	v_pk_mul_f32 v[10:11], v[10:11], v[130:131]
	v_mul_f32_e32 v130, 0xbfb8aa3b, v132
	v_mul_f32_e32 v131, 0xbfb8aa3b, v133
	v_add_f32_e32 v70, 1.0, v70
	v_add_f32_e32 v71, 1.0, v71
	v_rcp_f32_e32 v70, v70
	v_rcp_f32_e32 v71, v71
	v_exp_f32_e32 v130, v130
	v_exp_f32_e32 v131, v131
	v_pk_mul_f32 v[8:9], v[8:9], v[132:133]
	v_pk_mul_f32 v[10:11], v[70:71], v[10:11]
	v_add_f32_e32 v130, 1.0, v130
	v_add_f32_e32 v131, 1.0, v131
	v_rcp_f32_e32 v130, v130
	v_rcp_f32_e32 v131, v131
	v_cvt_pk_bf16_f32 v70, v10, v11
	s_nop 0
	v_pk_mul_f32 v[8:9], v[130:131], v[8:9]
	s_nop 0
	v_cvt_pk_bf16_f32 v71, v8, v9
	s_nop 1
	v_permlane16_swap_b32_e32 v68, v70
	v_permlane16_swap_b32_e32 v69, v71
	global_store_dwordx4 v[46:47], v[68:71], off offset:192
	s_barrier
	s_cbranch_scc1 .LBB0_438
	v_readlane_b32 s82, v255, 40
	v_readlane_b32 s4, v255, 38
	v_readlane_b32 s80, v255, 42
	v_readlane_b32 s83, v255, 41
	v_readlane_b32 s5, v255, 39
	v_readlane_b32 s2, v255, 58
	v_readlane_b32 s81, v255, 43
